# one static s_setprio 1 for the younger half (waves 4-7), set once per unit before each GEMM K-loop; no per-segment flips
# baseline (speedup 1.0000x reference)
; #define PG8_STAGE(bufoff, gbase, voff) do { _Pragma("unroll") for (int _i = 0; _i < 2; ++_i) \
;         __builtin_amdgcn_global_load_lds((const unsigned*)((const char*)(gbase) + (voff)[_i]), (LAS unsigned*)(lds + (bufoff) + ldsw + _i * 8192), 16, 0, 0); } while (0)
; #define PG8_LDA(dst, b, h) do { _Pragma("unroll") for (int m = 0; m < 4; ++m) _Pragma("unroll") for (int k = 0; k < 2; ++k) dst[m][k] = *(const LAS bf16x8*)(lds + PG8_SA(b, h) + aoff + m * 2048 + k * 1024); } while (0)
; #define PG8_LDB(dst, b, h) do { _Pragma("unroll") for (int n = 0; n < 2; ++n) _Pragma("unroll") for (int k = 0; k < 2; ++k) dst[n][k] = *(const LAS bf16x8*)(lds + PG8_SB(b, h) + boff + n * 2048 + k * 1024); } while (0)
; #define PG8_MMA(ai, bj, At, Bt) do { __builtin_amdgcn_s_setprio(1); _Pragma("unroll") for (int m = 0; m < 4; ++m) _Pragma("unroll") for (int n = 0; n < 2; ++n) _Pragma("unroll") for (int k = 0; k < 2; ++k) \
;         acc[ai][bj][m][n] = __builtin_amdgcn_mfma_f32_16x16x32_bf16(Bt[n][k], At[m][k], acc[ai][bj][m][n], 0, 0, 0); __builtin_amdgcn_s_setprio(0); } while (0)
; #define PG8_BAR __builtin_amdgcn_s_barrier()
; template <class Epi, class Sched = StaticOrder, class EpiSub = NoSub, bool FAST = false>
; __device__ __forceinline__ void gemm_phase(LAS unsigned char* lds, const Gemm g, const Sched& S, const Epi& E, const EpiSub& ES = EpiSub()) {
;     ...
;         const bool has_next = S.next(ui + 1, nxt);
;         const size_t nko = (has_next && nxt.kb >= 0) ? nxt.kb * ksubB : 0;
;         const char* nA = has_next ? (const char*)g.A + (size_t)nxt.pm * tstepA + (size_t)nxt.pn * g.acs + nko : cA; const char* nB = has_next ? (const char*)g.Bt + (size_t)nxt.pn * tstepB + nko : cB;
;         const int nt = cur.kb < 0 ? ntMain : ntSub;
;         for (int t = 0; t < nt; t += 2) {
;             const bool last = (t == nt - 2);
;             const char* a1 = cA + (size_t)(t + 1) * kstep;
;             const char* a2 = last ? nA : cA + (size_t)(t + 2) * kstep; const char* b2 = last ? nB : cB + (size_t)(t + 2) * kstep;
;             const char* a3 = a2 + kstep; const char* b3 = b2 + kstep;
;             if constexpr (FAST && PG8_SP2) {
;             PG8_LDB(B0, 0, 0); PG8_LDB(B1, 0, 1); PG8_SCHED; PG8_LDA(At, 0, 0); PG8_STAGE(PG8_SA(1, 1), a1 + hstepA, voffA);
;             PG8_WAIT_V(8); PG8_WAIT_L(0); PG8_BAR; PG8_MMA(0, 0, At, B0); PG8_MMA(0, 1, At, B1); PG8_BAR; PG8_SCHED;
.LBB0_215:
	s_ashr_i32 s15, s14, 31
	s_lshl_b64 s[2:3], s[14:15], 20
	v_readlane_b32 s16, v254, 36
	v_readlane_b32 s17, v254, 37
	s_add_u32 s16, s16, s2
	s_addc_u32 s17, s17, s3
	s_and_b64 s[2:3], s[0:1], exec
	s_cselect_b32 s2, s17, s23
	s_cselect_b32 s3, s16, s22
	s_ashr_i32 s13, s12, 31
	s_lshl_b64 s[18:19], s[12:13], 20
	s_add_u32 s18, s28, s18
	s_addc_u32 s19, s29, s19
	s_and_b64 s[26:27], s[0:1], exec
	s_cselect_b32 s13, s19, s25
	s_cselect_b32 s15, s18, s24
	s_add_u32 s22, s22, 0x80080
	s_addc_u32 s23, s23, 0
	s_add_u32 s48, s24, 0x100
	s_addc_u32 s49, s25, 0
	s_mov_b32 s50, -2
	s_cmp_eq_u64 s[10:11], 0
	s_cbranch_scc0 .Lkprio_216
	s_setprio 1
.Lkprio_216:
	ds_read_b128 v[154:157], v150
	ds_read_b128 v[158:161], v150 offset:1024
	ds_read_b128 v[162:165], v150 offset:2048
	ds_read_b128 v[166:169], v150 offset:3072
	ds_read_b128 v[170:173], v151
	ds_read_b128 v[174:177], v151 offset:1024
	ds_read_b128 v[178:181], v151 offset:2048
	ds_read_b128 v[182:185], v151 offset:3072
	s_add_u32 s24, s22, 0xfff80080
	s_addc_u32 s25, s23, -1
	s_cmp_eq_u32 s50, 28
	s_cselect_b32 s27, s2, s25
	s_cselect_b32 s26, s3, s24
	s_cselect_b32 s25, s13, s49
	s_cselect_b32 s24, s15, s48
	v_lshl_add_u64 v[144:145], s[22:23], 0, v[136:137]
	s_add_i32 m0, s21, 0xc000
	ds_read_b128 v[186:189], v152
	ds_read_b128 v[194:197], v152 offset:1024
	ds_read_b128 v[198:201], v152 offset:2048
	ds_read_b128 v[202:205], v152 offset:3072
	ds_read_b128 v[206:209], v152 offset:4096
	ds_read_b128 v[210:213], v152 offset:5120
	ds_read_b128 v[214:217], v152 offset:6144
	ds_read_b128 v[218:221], v152 offset:7168
	global_load_lds_dwordx4 v[144:145], off
	v_lshl_add_u64 v[144:145], s[22:23], 0, v[138:139]
	s_add_i32 m0, s21, 0xe000
	s_nop 0
	global_load_lds_dwordx4 v[144:145], off
	s_waitcnt vmcnt(8)
	s_waitcnt lgkmcnt(0)
	s_barrier
	v_mfma_f32_16x16x32_bf16 v[124:127], v[154:157], v[186:189], 0
	v_mfma_f32_16x16x32_bf16 v[120:123], v[162:165], v[186:189], 0
	v_mfma_f32_16x16x32_bf16 v[116:119], v[154:157], v[198:201], 0
	v_mfma_f32_16x16x32_bf16 v[108:111], v[162:165], v[198:201], 0
	v_mfma_f32_16x16x32_bf16 v[100:103], v[154:157], v[206:209], 0
	v_mfma_f32_16x16x32_bf16 v[92:95], v[162:165], v[206:209], 0
	v_mfma_f32_16x16x32_bf16 v[84:87], v[154:157], v[214:217], 0
	v_mfma_f32_16x16x32_bf16 v[76:79], v[162:165], v[214:217], 0
	v_mfma_f32_16x16x32_bf16 v[124:127], v[158:161], v[194:197], v[124:127]
	v_mfma_f32_16x16x32_bf16 v[120:123], v[166:169], v[194:197], v[120:123]
	v_mfma_f32_16x16x32_bf16 v[116:119], v[158:161], v[202:205], v[116:119]
	v_mfma_f32_16x16x32_bf16 v[108:111], v[166:169], v[202:205], v[108:111]
	v_mfma_f32_16x16x32_bf16 v[100:103], v[158:161], v[210:213], v[100:103]
	v_mfma_f32_16x16x32_bf16 v[92:95], v[166:169], v[210:213], v[92:95]
	v_mfma_f32_16x16x32_bf16 v[84:87], v[158:161], v[218:221], v[84:87]
	v_mfma_f32_16x16x32_bf16 v[76:79], v[166:169], v[218:221], v[76:79]
	v_mfma_f32_16x16x32_bf16 v[112:115], v[170:173], v[186:189], 0
	v_mfma_f32_16x16x32_bf16 v[104:107], v[178:181], v[186:189], 0
	v_mfma_f32_16x16x32_bf16 v[96:99], v[170:173], v[198:201], 0
	v_mfma_f32_16x16x32_bf16 v[88:91], v[178:181], v[198:201], 0
	v_mfma_f32_16x16x32_bf16 v[80:83], v[170:173], v[206:209], 0
	v_mfma_f32_16x16x32_bf16 v[72:75], v[178:181], v[206:209], 0
	v_mfma_f32_16x16x32_bf16 v[68:71], v[170:173], v[214:217], 0
	v_mfma_f32_16x16x32_bf16 v[64:67], v[178:181], v[214:217], 0
	v_mfma_f32_16x16x32_bf16 v[112:115], v[174:177], v[194:197], v[112:115]
	v_mfma_f32_16x16x32_bf16 v[104:107], v[182:185], v[194:197], v[104:107]
	v_mfma_f32_16x16x32_bf16 v[96:99], v[174:177], v[202:205], v[96:99]
	v_mfma_f32_16x16x32_bf16 v[88:91], v[182:185], v[202:205], v[88:91]
	v_mfma_f32_16x16x32_bf16 v[80:83], v[174:177], v[210:213], v[80:83]
	v_mfma_f32_16x16x32_bf16 v[72:75], v[182:185], v[210:213], v[72:75]
	v_mfma_f32_16x16x32_bf16 v[68:71], v[174:177], v[218:221], v[68:71]
	v_mfma_f32_16x16x32_bf16 v[64:67], v[182:185], v[218:221], v[64:67]
	s_barrier
	s_add_i32 s51, s41, s30
	v_lshl_add_u64 v[144:145], s[24:25], 0, v[130:131]
	s_mov_b32 m0, s51
	ds_read_b128 v[186:189], v152 offset:16384
	ds_read_b128 v[194:197], v152 offset:17408
	ds_read_b128 v[198:201], v152 offset:18432
	ds_read_b128 v[202:205], v152 offset:19456
	ds_read_b128 v[206:209], v152 offset:20480
	ds_read_b128 v[210:213], v152 offset:21504
	ds_read_b128 v[214:217], v152 offset:22528
	ds_read_b128 v[218:221], v152 offset:23552
	global_load_lds_dwordx4 v[144:145], off
	s_add_i32 m0, s51, 0x2000
	s_add_u32 s68, s24, 0x80000
	v_lshl_add_u64 v[190:191], s[24:25], 0, v[134:135]
	s_addc_u32 s69, s25, 0
	s_add_i32 s51, s42, s30
	global_load_lds_dwordx4 v[190:191], off
	v_lshl_add_u64 v[222:223], s[68:69], 0, v[130:131]
	s_mov_b32 m0, s51
	v_lshl_add_u64 v[224:225], s[26:27], 0, v[132:133]
	global_load_lds_dwordx4 v[222:223], off
	v_lshl_add_u64 v[222:223], s[68:69], 0, v[134:135]
	s_add_i32 m0, s51, 0x2000
	s_nop 0
	global_load_lds_dwordx4 v[222:223], off
	v_lshl_add_u64 v[222:223], s[26:27], 0, v[128:129]
	s_mov_b32 m0, s21
	s_nop 0
	global_load_lds_dwordx4 v[222:223], off
	s_mov_b32 m0, s34
	s_nop 0
	global_load_lds_dwordx4 v[224:225], off
	s_waitcnt vmcnt(8)
	s_waitcnt lgkmcnt(0)
	s_barrier
; #define PG8_STAGE(bufoff, gbase, voff) do { _Pragma("unroll") for (int _i = 0; _i < 2; ++_i) \
;         __builtin_amdgcn_global_load_lds((const unsigned*)((const char*)(gbase) + (voff)[_i]), (LAS unsigned*)(lds + (bufoff) + ldsw + _i * 8192), 16, 0, 0); } while (0)
; #define PG8_LDA(dst, b, h) do { _Pragma("unroll") for (int m = 0; m < 4; ++m) _Pragma("unroll") for (int k = 0; k < 2; ++k) dst[m][k] = *(const LAS bf16x8*)(lds + PG8_SA(b, h) + aoff + m * 2048 + k * 1024); } while (0)
; #define PG8_LDB(dst, b, h) do { _Pragma("unroll") for (int n = 0; n < 2; ++n) _Pragma("unroll") for (int k = 0; k < 2; ++k) dst[n][k] = *(const LAS bf16x8*)(lds + PG8_SB(b, h) + boff + n * 2048 + k * 1024); } while (0)
; #define PG8_MMA(ai, bj, At, Bt) do { __builtin_amdgcn_s_setprio(1); _Pragma("unroll") for (int m = 0; m < 4; ++m) _Pragma("unroll") for (int n = 0; n < 2; ++n) _Pragma("unroll") for (int k = 0; k < 2; ++k) \
;         acc[ai][bj][m][n] = __builtin_amdgcn_mfma_f32_16x16x32_bf16(Bt[n][k], At[m][k], acc[ai][bj][m][n], 0, 0, 0); __builtin_amdgcn_s_setprio(0); } while (0)
; #define PG8_WAIT_V(n) asm volatile("s_waitcnt vmcnt(" #n ")" ::: "memory")
; #define PG8_WAIT_L(n) asm volatile("s_waitcnt lgkmcnt(" #n ")" ::: "memory")
; #define PG8_BAR __builtin_amdgcn_s_barrier()
; #define PG8_SCHED __builtin_amdgcn_sched_barrier(0)
; template <class Epi, class Sched = StaticOrder, class EpiSub = NoSub, bool FAST = false>
; __device__ __forceinline__ void gemm_phase(LAS unsigned char* lds, const Gemm g, const Sched& S, const Epi& E, const EpiSub& ES = EpiSub()) {
;     ...
;             PG8_WAIT_V(8); PG8_WAIT_L(0); PG8_BAR; PG8_MMA(0, 0, At, B0); PG8_MMA(0, 1, At, B1); PG8_BAR; PG8_SCHED;
;             PG8_LDA(At, 0, 1); PG8_STAGE(PG8_SB(0, 0), b2, voffB); PG8_STAGE(PG8_SB(0, 1), b2 + hstepB, voffB); PG8_STAGE(PG8_SA(0, 0), a2, voffA);
;             PG8_WAIT_V(8); PG8_WAIT_L(0); PG8_BAR; PG8_MMA(1, 0, At, B0); PG8_MMA(1, 1, At, B1); PG8_BAR; PG8_SCHED;
;             PG8_LDB(B0, 1, 0); PG8_LDB(B1, 1, 1); PG8_SCHED; PG8_LDA(At, 1, 0); PG8_STAGE(PG8_SA(0, 1), a2 + hstepA, voffA);
;             PG8_WAIT_V(8); PG8_WAIT_L(0); PG8_BAR; PG8_MMA(0, 0, At, B0); PG8_MMA(0, 1, At, B1); PG8_BAR; PG8_SCHED;
	v_mfma_f32_16x16x32_bf16 v[60:63], v[154:157], v[186:189], 0
	v_mfma_f32_16x16x32_bf16 v[56:59], v[162:165], v[186:189], 0
	v_mfma_f32_16x16x32_bf16 v[52:55], v[154:157], v[198:201], 0
	v_mfma_f32_16x16x32_bf16 v[44:47], v[162:165], v[198:201], 0
	v_mfma_f32_16x16x32_bf16 v[36:39], v[154:157], v[206:209], 0
	v_mfma_f32_16x16x32_bf16 v[28:31], v[162:165], v[206:209], 0
	v_mfma_f32_16x16x32_bf16 v[20:23], v[154:157], v[214:217], 0
	v_mfma_f32_16x16x32_bf16 v[12:15], v[162:165], v[214:217], 0
	v_mfma_f32_16x16x32_bf16 v[60:63], v[158:161], v[194:197], v[60:63]
	v_mfma_f32_16x16x32_bf16 v[56:59], v[166:169], v[194:197], v[56:59]
	v_mfma_f32_16x16x32_bf16 v[52:55], v[158:161], v[202:205], v[52:55]
	v_mfma_f32_16x16x32_bf16 v[44:47], v[166:169], v[202:205], v[44:47]
	v_mfma_f32_16x16x32_bf16 v[36:39], v[158:161], v[210:213], v[36:39]
	v_mfma_f32_16x16x32_bf16 v[28:31], v[166:169], v[210:213], v[28:31]
	v_mfma_f32_16x16x32_bf16 v[20:23], v[158:161], v[218:221], v[20:23]
	v_mfma_f32_16x16x32_bf16 v[12:15], v[166:169], v[218:221], v[12:15]
	v_mfma_f32_16x16x32_bf16 v[48:51], v[170:173], v[186:189], 0
	v_mfma_f32_16x16x32_bf16 v[40:43], v[178:181], v[186:189], 0
	v_mfma_f32_16x16x32_bf16 v[32:35], v[170:173], v[198:201], 0
	v_mfma_f32_16x16x32_bf16 v[24:27], v[178:181], v[198:201], 0
	v_mfma_f32_16x16x32_bf16 v[16:19], v[170:173], v[206:209], 0
	v_mfma_f32_16x16x32_bf16 v[8:11], v[178:181], v[206:209], 0
	v_mfma_f32_16x16x32_bf16 v[4:7], v[170:173], v[214:217], 0
	v_mfma_f32_16x16x32_bf16 v[0:3], v[178:181], v[214:217], 0
	v_mfma_f32_16x16x32_bf16 v[48:51], v[174:177], v[194:197], v[48:51]
	v_mfma_f32_16x16x32_bf16 v[40:43], v[182:185], v[194:197], v[40:43]
	v_mfma_f32_16x16x32_bf16 v[32:35], v[174:177], v[202:205], v[32:35]
	v_mfma_f32_16x16x32_bf16 v[24:27], v[182:185], v[202:205], v[24:27]
	v_mfma_f32_16x16x32_bf16 v[16:19], v[174:177], v[210:213], v[16:19]
	v_mfma_f32_16x16x32_bf16 v[8:11], v[182:185], v[210:213], v[8:11]
	v_mfma_f32_16x16x32_bf16 v[4:7], v[174:177], v[218:221], v[4:7]
	v_mfma_f32_16x16x32_bf16 v[0:3], v[182:185], v[218:221], v[0:3]
	s_barrier
	s_add_i32 s51, 0, 0x18000
	v_add_u32_e32 v153, s51, v148
	s_add_i32 s68, 0, 0x1c000
	ds_read_b128 v[154:157], v153
	ds_read_b128 v[158:161], v153 offset:1024
	ds_read_b128 v[162:165], v153 offset:2048
	ds_read_b128 v[166:169], v153 offset:3072
	v_add_u32_e32 v153, s68, v148
	ds_read_b128 v[170:173], v153
	ds_read_b128 v[174:177], v153 offset:1024
	ds_read_b128 v[178:181], v153 offset:2048
	ds_read_b128 v[182:185], v153 offset:3072
	s_add_u32 s26, s26, 0x80000
	s_addc_u32 s27, s27, 0
	s_mov_b32 m0, s35
	v_lshl_add_u64 v[226:227], s[26:27], 0, v[128:129]
	ds_read_b128 v[186:189], v152 offset:32768
	ds_read_b128 v[194:197], v152 offset:33792
	ds_read_b128 v[198:201], v152 offset:34816
	ds_read_b128 v[202:205], v152 offset:35840
	ds_read_b128 v[206:209], v152 offset:36864
	ds_read_b128 v[210:213], v152 offset:37888
	ds_read_b128 v[214:217], v152 offset:38912
	ds_read_b128 v[218:221], v152 offset:39936
	global_load_lds_dwordx4 v[226:227], off
	v_lshl_add_u64 v[226:227], s[26:27], 0, v[132:133]
	s_mov_b32 m0, s36
	s_nop 0
	global_load_lds_dwordx4 v[226:227], off
	s_waitcnt vmcnt(8)
	s_waitcnt lgkmcnt(0)
	s_barrier
	v_mfma_f32_16x16x32_bf16 v[124:127], v[154:157], v[186:189], v[124:127]
	v_mfma_f32_16x16x32_bf16 v[120:123], v[162:165], v[186:189], v[120:123]
	v_mfma_f32_16x16x32_bf16 v[116:119], v[154:157], v[198:201], v[116:119]
	v_mfma_f32_16x16x32_bf16 v[108:111], v[162:165], v[198:201], v[108:111]
	v_mfma_f32_16x16x32_bf16 v[100:103], v[154:157], v[206:209], v[100:103]
	v_mfma_f32_16x16x32_bf16 v[92:95], v[162:165], v[206:209], v[92:95]
	v_mfma_f32_16x16x32_bf16 v[84:87], v[154:157], v[214:217], v[84:87]
	v_mfma_f32_16x16x32_bf16 v[76:79], v[162:165], v[214:217], v[76:79]
	v_mfma_f32_16x16x32_bf16 v[124:127], v[158:161], v[194:197], v[124:127]
	v_mfma_f32_16x16x32_bf16 v[120:123], v[166:169], v[194:197], v[120:123]
	v_mfma_f32_16x16x32_bf16 v[116:119], v[158:161], v[202:205], v[116:119]
	v_mfma_f32_16x16x32_bf16 v[108:111], v[166:169], v[202:205], v[108:111]
	v_mfma_f32_16x16x32_bf16 v[100:103], v[158:161], v[210:213], v[100:103]
	v_mfma_f32_16x16x32_bf16 v[92:95], v[166:169], v[210:213], v[92:95]
	v_mfma_f32_16x16x32_bf16 v[84:87], v[158:161], v[218:221], v[84:87]
	v_mfma_f32_16x16x32_bf16 v[76:79], v[166:169], v[218:221], v[76:79]
	v_mfma_f32_16x16x32_bf16 v[112:115], v[170:173], v[186:189], v[112:115]
	v_mfma_f32_16x16x32_bf16 v[104:107], v[178:181], v[186:189], v[104:107]
	v_mfma_f32_16x16x32_bf16 v[96:99], v[170:173], v[198:201], v[96:99]
	v_mfma_f32_16x16x32_bf16 v[88:91], v[178:181], v[198:201], v[88:91]
	v_mfma_f32_16x16x32_bf16 v[80:83], v[170:173], v[206:209], v[80:83]
	v_mfma_f32_16x16x32_bf16 v[72:75], v[178:181], v[206:209], v[72:75]
	v_mfma_f32_16x16x32_bf16 v[68:71], v[170:173], v[214:217], v[68:71]
	v_mfma_f32_16x16x32_bf16 v[64:67], v[178:181], v[214:217], v[64:67]
	v_mfma_f32_16x16x32_bf16 v[112:115], v[174:177], v[194:197], v[112:115]
	v_mfma_f32_16x16x32_bf16 v[104:107], v[182:185], v[194:197], v[104:107]
	v_mfma_f32_16x16x32_bf16 v[96:99], v[174:177], v[202:205], v[96:99]
	v_mfma_f32_16x16x32_bf16 v[88:91], v[182:185], v[202:205], v[88:91]
	v_mfma_f32_16x16x32_bf16 v[80:83], v[174:177], v[210:213], v[80:83]
	v_mfma_f32_16x16x32_bf16 v[72:75], v[182:185], v[210:213], v[72:75]
	v_mfma_f32_16x16x32_bf16 v[68:71], v[174:177], v[218:221], v[68:71]
	v_mfma_f32_16x16x32_bf16 v[64:67], v[182:185], v[218:221], v[64:67]
	s_barrier
; #define PG8_STAGE(bufoff, gbase, voff) do { _Pragma("unroll") for (int _i = 0; _i < 2; ++_i) \
;         __builtin_amdgcn_global_load_lds((const unsigned*)((const char*)(gbase) + (voff)[_i]), (LAS unsigned*)(lds + (bufoff) + ldsw + _i * 8192), 16, 0, 0); } while (0)
; #define PG8_LDA(dst, b, h) do { _Pragma("unroll") for (int m = 0; m < 4; ++m) _Pragma("unroll") for (int k = 0; k < 2; ++k) dst[m][k] = *(const LAS bf16x8*)(lds + PG8_SA(b, h) + aoff + m * 2048 + k * 1024); } while (0)
; #define PG8_MMA(ai, bj, At, Bt) do { __builtin_amdgcn_s_setprio(1); _Pragma("unroll") for (int m = 0; m < 4; ++m) _Pragma("unroll") for (int n = 0; n < 2; ++n) _Pragma("unroll") for (int k = 0; k < 2; ++k) \
;         acc[ai][bj][m][n] = __builtin_amdgcn_mfma_f32_16x16x32_bf16(Bt[n][k], At[m][k], acc[ai][bj][m][n], 0, 0, 0); __builtin_amdgcn_s_setprio(0); } while (0)
; #define PG8_WAIT_V(n) asm volatile("s_waitcnt vmcnt(" #n ")" ::: "memory")
; #define PG8_WAIT_L(n) asm volatile("s_waitcnt lgkmcnt(" #n ")" ::: "memory")
; #define PG8_BAR __builtin_amdgcn_s_barrier()
; #define PG8_SCHED __builtin_amdgcn_sched_barrier(0)
; template <class Epi, class Sched = StaticOrder, class EpiSub = NoSub, bool FAST = false>
; __device__ __forceinline__ void gemm_phase(LAS unsigned char* lds, const Gemm g, const Sched& S, const Epi& E, const EpiSub& ES = EpiSub()) {
;     ...
;             PG8_WAIT_V(8); PG8_WAIT_L(0); PG8_BAR; PG8_MMA(0, 0, At, B0); PG8_MMA(0, 1, At, B1); PG8_BAR; PG8_SCHED;
;             PG8_LDA(At, 1, 1); PG8_STAGE(PG8_SB(1, 0), b3, voffB); PG8_STAGE(PG8_SB(1, 1), b3 + hstepB, voffB); PG8_STAGE(PG8_SA(1, 0), a3, voffA);
;             PG8_WAIT_V(8); PG8_WAIT_L(0); PG8_BAR; PG8_MMA(1, 0, At, B0); PG8_MMA(1, 1, At, B1); PG8_BAR; PG8_SCHED;
	s_add_i32 s26, s51, s30
	v_lshl_add_u64 v[144:145], v[144:145], 0, s[8:9]
	s_mov_b32 m0, s26
	ds_read_b128 v[186:189], v152 offset:49152
	ds_read_b128 v[194:197], v152 offset:50176
	ds_read_b128 v[198:201], v152 offset:51200
	ds_read_b128 v[202:205], v152 offset:52224
	ds_read_b128 v[206:209], v152 offset:53248
	ds_read_b128 v[210:213], v152 offset:54272
	ds_read_b128 v[214:217], v152 offset:55296
	ds_read_b128 v[218:221], v152 offset:56320
	global_load_lds_dwordx4 v[144:145], off
	s_add_i32 m0, s26, 0x2000
	s_add_u32 s24, s24, 0x80080
	v_lshl_add_u64 v[144:145], v[190:191], 0, s[8:9]
	s_addc_u32 s25, s25, 0
	s_add_i32 s26, s68, s30
	global_load_lds_dwordx4 v[144:145], off
	v_lshl_add_u64 v[144:145], s[24:25], 0, v[130:131]
	s_mov_b32 m0, s26
	s_nop 0
	global_load_lds_dwordx4 v[144:145], off
	v_lshl_add_u64 v[144:145], s[24:25], 0, v[134:135]
	s_add_i32 m0, s26, 0x2000
	s_nop 0
	global_load_lds_dwordx4 v[144:145], off
	v_lshl_add_u64 v[144:145], v[222:223], 0, s[8:9]
	s_mov_b32 m0, s39
	s_nop 0
	global_load_lds_dwordx4 v[144:145], off
	v_lshl_add_u64 v[144:145], v[224:225], 0, s[8:9]
	s_mov_b32 m0, s40
	s_nop 0
	global_load_lds_dwordx4 v[144:145], off
	s_waitcnt vmcnt(8)
	s_waitcnt lgkmcnt(0)
	s_barrier
	v_mfma_f32_16x16x32_bf16 v[60:63], v[154:157], v[186:189], v[60:63]
	v_mfma_f32_16x16x32_bf16 v[56:59], v[162:165], v[186:189], v[56:59]
	v_mfma_f32_16x16x32_bf16 v[52:55], v[154:157], v[198:201], v[52:55]
	v_mfma_f32_16x16x32_bf16 v[44:47], v[162:165], v[198:201], v[44:47]
	v_mfma_f32_16x16x32_bf16 v[36:39], v[154:157], v[206:209], v[36:39]
	v_mfma_f32_16x16x32_bf16 v[28:31], v[162:165], v[206:209], v[28:31]
	v_mfma_f32_16x16x32_bf16 v[20:23], v[154:157], v[214:217], v[20:23]
	v_mfma_f32_16x16x32_bf16 v[12:15], v[162:165], v[214:217], v[12:15]
	v_mfma_f32_16x16x32_bf16 v[60:63], v[158:161], v[194:197], v[60:63]
	v_mfma_f32_16x16x32_bf16 v[56:59], v[166:169], v[194:197], v[56:59]
	v_mfma_f32_16x16x32_bf16 v[52:55], v[158:161], v[202:205], v[52:55]
	v_mfma_f32_16x16x32_bf16 v[44:47], v[166:169], v[202:205], v[44:47]
	v_mfma_f32_16x16x32_bf16 v[36:39], v[158:161], v[210:213], v[36:39]
	v_mfma_f32_16x16x32_bf16 v[28:31], v[166:169], v[210:213], v[28:31]
	v_mfma_f32_16x16x32_bf16 v[20:23], v[158:161], v[218:221], v[20:23]
	v_mfma_f32_16x16x32_bf16 v[12:15], v[166:169], v[218:221], v[12:15]
	v_mfma_f32_16x16x32_bf16 v[48:51], v[170:173], v[186:189], v[48:51]
	v_mfma_f32_16x16x32_bf16 v[40:43], v[178:181], v[186:189], v[40:43]
	v_mfma_f32_16x16x32_bf16 v[32:35], v[170:173], v[198:201], v[32:35]
	v_mfma_f32_16x16x32_bf16 v[24:27], v[178:181], v[198:201], v[24:27]
	v_mfma_f32_16x16x32_bf16 v[16:19], v[170:173], v[206:209], v[16:19]
	v_mfma_f32_16x16x32_bf16 v[8:11], v[178:181], v[206:209], v[8:11]
	v_mfma_f32_16x16x32_bf16 v[4:7], v[170:173], v[214:217], v[4:7]
	v_mfma_f32_16x16x32_bf16 v[0:3], v[178:181], v[214:217], v[0:3]
	v_mfma_f32_16x16x32_bf16 v[48:51], v[174:177], v[194:197], v[48:51]
	v_mfma_f32_16x16x32_bf16 v[40:43], v[182:185], v[194:197], v[40:43]
	v_mfma_f32_16x16x32_bf16 v[32:35], v[174:177], v[202:205], v[32:35]
	v_mfma_f32_16x16x32_bf16 v[24:27], v[182:185], v[202:205], v[24:27]
	v_mfma_f32_16x16x32_bf16 v[16:19], v[174:177], v[210:213], v[16:19]
	v_mfma_f32_16x16x32_bf16 v[8:11], v[182:185], v[210:213], v[8:11]
	v_mfma_f32_16x16x32_bf16 v[4:7], v[174:177], v[218:221], v[4:7]
	v_mfma_f32_16x16x32_bf16 v[0:3], v[182:185], v[218:221], v[0:3]
	s_barrier
	s_add_i32 s50, s50, 2
	s_add_u32 s22, s22, 0x100
	s_addc_u32 s23, s23, 0
	s_add_u32 s48, s48, 0x100
	s_addc_u32 s49, s49, 0
	s_cmp_gt_u32 s50, 29
	s_cbranch_scc1 .Lkpeel_216_exit

; #define PG8_STAGE(bufoff, gbase, voff) do { _Pragma("unroll") for (int _i = 0; _i < 2; ++_i) \
;         __builtin_amdgcn_global_load_lds((const unsigned*)((const char*)(gbase) + (voff)[_i]), (LAS unsigned*)(lds + (bufoff) + ldsw + _i * 8192), 16, 0, 0); } while (0)
; #define PG8_LDA(dst, b, h) do { _Pragma("unroll") for (int m = 0; m < 4; ++m) _Pragma("unroll") for (int k = 0; k < 2; ++k) dst[m][k] = *(const LAS bf16x8*)(lds + PG8_SA(b, h) + aoff + m * 2048 + k * 1024); } while (0)
; #define PG8_LDB(dst, b, h) do { _Pragma("unroll") for (int n = 0; n < 2; ++n) _Pragma("unroll") for (int k = 0; k < 2; ++k) dst[n][k] = *(const LAS bf16x8*)(lds + PG8_SB(b, h) + boff + n * 2048 + k * 1024); } while (0)
; #define PG8_MMA(ai, bj, At, Bt) do { __builtin_amdgcn_s_setprio(1); _Pragma("unroll") for (int m = 0; m < 4; ++m) _Pragma("unroll") for (int n = 0; n < 2; ++n) _Pragma("unroll") for (int k = 0; k < 2; ++k) \
;         acc[ai][bj][m][n] = __builtin_amdgcn_mfma_f32_16x16x32_bf16(Bt[n][k], At[m][k], acc[ai][bj][m][n], 0, 0, 0); __builtin_amdgcn_s_setprio(0); } while (0)
; #define PG8_BAR __builtin_amdgcn_s_barrier()
; template <class Epi, class Sched = StaticOrder, class EpiSub = NoSub, bool FAST = false>
; __device__ __forceinline__ void gemm_phase(LAS unsigned char* lds, const Gemm g, const Sched& S, const Epi& E, const EpiSub& ES = EpiSub()) {
;     ...
;         const bool has_next = S.next(ui + 1, nxt);
;         const size_t nko = (has_next && nxt.kb >= 0) ? nxt.kb * ksubB : 0;
;         const char* nA = has_next ? (const char*)g.A + (size_t)nxt.pm * tstepA + (size_t)nxt.pn * g.acs + nko : cA; const char* nB = has_next ? (const char*)g.Bt + (size_t)nxt.pn * tstepB + nko : cB;
;         const int nt = cur.kb < 0 ? ntMain : ntSub;
;         for (int t = 0; t < nt; t += 2) {
;             const bool last = (t == nt - 2);
;             const char* a1 = cA + (size_t)(t + 1) * kstep;
;             const char* a2 = last ? nA : cA + (size_t)(t + 2) * kstep; const char* b2 = last ? nB : cB + (size_t)(t + 2) * kstep;
;             const char* a3 = a2 + kstep; const char* b3 = b2 + kstep;
;             if constexpr (FAST && PG8_SP2) {
;             PG8_LDB(B0, 0, 0); PG8_LDB(B1, 0, 1); PG8_SCHED; PG8_LDA(At, 0, 0); PG8_STAGE(PG8_SA(1, 1), a1 + hstepA, voffA);
;             PG8_WAIT_V(8); PG8_WAIT_L(0); PG8_BAR; PG8_MMA(0, 0, At, B0); PG8_MMA(0, 1, At, B1); PG8_BAR; PG8_SCHED;
.LBB0_599:
	s_cmp_gt_i32 s8, -1
	s_cselect_b64 s[30:31], -1, 0
	s_and_b64 s[30:31], s[28:29], s[30:31]
	s_lshl_b64 s[36:37], s[8:9], 9
	s_and_b64 s[30:31], s[30:31], exec
	s_cselect_b32 s7, s37, 0
	s_cselect_b32 s33, s36, 0
	s_ashr_i32 s27, s26, 31
	s_lshl_b64 s[30:31], s[26:27], 19
	s_add_u32 s1, s78, s30
	s_addc_u32 s5, s79, s31
	s_add_u32 s30, s1, s33
	s_addc_u32 s31, s5, s7
	s_and_b64 s[36:37], s[28:29], exec
	s_cselect_b32 s1, s31, s41
	s_cselect_b32 s5, s30, s40
	s_ashr_i32 s25, s24, 31
	s_lshl_b64 s[36:37], s[24:25], 19
	s_add_u32 s25, s2, s36
	s_addc_u32 s27, s3, s37
	s_add_u32 s36, s25, s33
	s_addc_u32 s37, s27, s7
	s_and_b64 s[38:39], s[28:29], exec
	s_cselect_b32 s7, s37, s43
	s_cselect_b32 s25, s36, s42
	s_cmp_gt_i32 s0, -1
	s_cselect_b64 s[38:39], -1, 0
	s_cmp_lt_i32 s0, 0
	s_cselect_b32 s27, 16, 4
	s_add_i32 s33, s27, -2
	s_add_u32 s40, s40, 0x40080
	s_addc_u32 s41, s41, 0
	s_add_u32 s48, s42, 0x100
	s_mov_b32 s50, 0
	s_addc_u32 s49, s43, 0
	s_cmp_eq_u64 s[14:15], 0
	s_cbranch_scc0 .Lkprio_600
	s_setprio 1
.Lkprio_600:
	ds_read_b128 v[100:103], v186
	ds_read_b128 v[112:115], v186 offset:1024
	ds_read_b128 v[124:127], v186 offset:2048
	ds_read_b128 v[136:139], v186 offset:3072
	ds_read_b128 v[144:147], v187
	ds_read_b128 v[148:151], v187 offset:1024
	ds_read_b128 v[152:155], v187 offset:2048
	ds_read_b128 v[170:173], v187 offset:3072
	s_add_i32 s51, s50, 2
	s_add_u32 s42, s40, 0xfffc0080
	s_addc_u32 s43, s41, -1
	s_cmp_eq_u32 s33, s50
	s_cselect_b32 s53, s1, s43
	s_cselect_b32 s52, s5, s42
	s_cselect_b32 s43, s7, s49
	s_cselect_b32 s42, s25, s48
	v_lshl_add_u64 v[190:191], s[40:41], 0, v[164:165]
	s_add_i32 m0, s55, 0xc000
	ds_read_b128 v[174:177], v188
	ds_read_b128 v[178:181], v188 offset:1024
	ds_read_b128 v[194:197], v188 offset:2048
	ds_read_b128 v[198:201], v188 offset:3072
	ds_read_b128 v[202:205], v188 offset:4096
	ds_read_b128 v[206:209], v188 offset:5120
	ds_read_b128 v[210:213], v188 offset:6144
	ds_read_b128 v[214:217], v188 offset:7168
	global_load_lds_dwordx4 v[190:191], off
	v_lshl_add_u64 v[190:191], s[40:41], 0, v[166:167]
	s_add_i32 m0, s55, 0xe000
	s_nop 0
	global_load_lds_dwordx4 v[190:191], off
	s_waitcnt vmcnt(8)
	s_waitcnt lgkmcnt(0)
	s_barrier
	v_mfma_f32_16x16x32_bf16 v[140:143], v[100:103], v[174:177], 0
	v_mfma_f32_16x16x32_bf16 v[132:135], v[124:127], v[174:177], 0
	v_mfma_f32_16x16x32_bf16 v[116:119], v[100:103], v[194:197], 0
	v_mfma_f32_16x16x32_bf16 v[108:111], v[124:127], v[194:197], 0
	v_mfma_f32_16x16x32_bf16 v[92:95], v[100:103], v[202:205], 0
	v_mfma_f32_16x16x32_bf16 v[88:91], v[124:127], v[202:205], 0
	v_mfma_f32_16x16x32_bf16 v[76:79], v[100:103], v[210:213], 0
	v_mfma_f32_16x16x32_bf16 v[72:75], v[124:127], v[210:213], 0
	v_mfma_f32_16x16x32_bf16 v[140:143], v[112:115], v[178:181], v[140:143]
	v_mfma_f32_16x16x32_bf16 v[132:135], v[136:139], v[178:181], v[132:135]
	v_mfma_f32_16x16x32_bf16 v[116:119], v[112:115], v[198:201], v[116:119]
	v_mfma_f32_16x16x32_bf16 v[108:111], v[136:139], v[198:201], v[108:111]
	v_mfma_f32_16x16x32_bf16 v[92:95], v[112:115], v[206:209], v[92:95]
	v_mfma_f32_16x16x32_bf16 v[88:91], v[136:139], v[206:209], v[88:91]
	v_mfma_f32_16x16x32_bf16 v[76:79], v[112:115], v[214:217], v[76:79]
	v_mfma_f32_16x16x32_bf16 v[72:75], v[136:139], v[214:217], v[72:75]
	v_mfma_f32_16x16x32_bf16 v[128:131], v[144:147], v[174:177], 0
	v_mfma_f32_16x16x32_bf16 v[120:123], v[152:155], v[174:177], 0
	v_mfma_f32_16x16x32_bf16 v[104:107], v[144:147], v[194:197], 0
	v_mfma_f32_16x16x32_bf16 v[96:99], v[152:155], v[194:197], 0
	v_mfma_f32_16x16x32_bf16 v[84:87], v[144:147], v[202:205], 0
	v_mfma_f32_16x16x32_bf16 v[80:83], v[152:155], v[202:205], 0
	v_mfma_f32_16x16x32_bf16 v[68:71], v[144:147], v[210:213], 0
	v_mfma_f32_16x16x32_bf16 v[64:67], v[152:155], v[210:213], 0
	v_mfma_f32_16x16x32_bf16 v[128:131], v[148:151], v[178:181], v[128:131]
	v_mfma_f32_16x16x32_bf16 v[120:123], v[170:173], v[178:181], v[120:123]
	v_mfma_f32_16x16x32_bf16 v[104:107], v[148:151], v[198:201], v[104:107]
	v_mfma_f32_16x16x32_bf16 v[96:99], v[170:173], v[198:201], v[96:99]
	v_mfma_f32_16x16x32_bf16 v[84:87], v[148:151], v[206:209], v[84:87]
	v_mfma_f32_16x16x32_bf16 v[80:83], v[170:173], v[206:209], v[80:83]
	v_mfma_f32_16x16x32_bf16 v[68:71], v[148:151], v[214:217], v[68:71]
	v_mfma_f32_16x16x32_bf16 v[64:67], v[170:173], v[214:217], v[64:67]
	s_barrier
	s_add_i32 s50, s75, s54
	v_lshl_add_u64 v[190:191], s[42:43], 0, v[158:159]
	s_mov_b32 m0, s50
	ds_read_b128 v[174:177], v188 offset:16384
	ds_read_b128 v[178:181], v188 offset:17408
	ds_read_b128 v[194:197], v188 offset:18432
	ds_read_b128 v[198:201], v188 offset:19456
	ds_read_b128 v[202:205], v188 offset:20480
	ds_read_b128 v[206:209], v188 offset:21504
	ds_read_b128 v[210:213], v188 offset:22528
	ds_read_b128 v[214:217], v188 offset:23552
	global_load_lds_dwordx4 v[190:191], off
	s_add_i32 m0, s50, 0x2000
	s_add_u32 s70, s42, 0x40000
	v_lshl_add_u64 v[218:219], s[42:43], 0, v[162:163]
	s_addc_u32 s71, s43, 0
	s_add_i32 s50, s80, s54
	global_load_lds_dwordx4 v[218:219], off
	v_lshl_add_u64 v[220:221], s[70:71], 0, v[158:159]
	s_mov_b32 m0, s50
	v_lshl_add_u64 v[222:223], s[52:53], 0, v[160:161]
	global_load_lds_dwordx4 v[220:221], off
	v_lshl_add_u64 v[220:221], s[70:71], 0, v[162:163]
	s_add_i32 m0, s50, 0x2000
	s_nop 0
	global_load_lds_dwordx4 v[220:221], off
	v_lshl_add_u64 v[220:221], s[52:53], 0, v[156:157]
	s_mov_b32 m0, s55
	s_nop 0
	global_load_lds_dwordx4 v[220:221], off
	s_mov_b32 m0, s56
	s_nop 0
	global_load_lds_dwordx4 v[222:223], off
	s_waitcnt vmcnt(8)
	s_waitcnt lgkmcnt(0)
	s_barrier
; #define PG8_STAGE(bufoff, gbase, voff) do { _Pragma("unroll") for (int _i = 0; _i < 2; ++_i) \
;         __builtin_amdgcn_global_load_lds((const unsigned*)((const char*)(gbase) + (voff)[_i]), (LAS unsigned*)(lds + (bufoff) + ldsw + _i * 8192), 16, 0, 0); } while (0)
; #define PG8_LDA(dst, b, h) do { _Pragma("unroll") for (int m = 0; m < 4; ++m) _Pragma("unroll") for (int k = 0; k < 2; ++k) dst[m][k] = *(const LAS bf16x8*)(lds + PG8_SA(b, h) + aoff + m * 2048 + k * 1024); } while (0)
; #define PG8_LDB(dst, b, h) do { _Pragma("unroll") for (int n = 0; n < 2; ++n) _Pragma("unroll") for (int k = 0; k < 2; ++k) dst[n][k] = *(const LAS bf16x8*)(lds + PG8_SB(b, h) + boff + n * 2048 + k * 1024); } while (0)
; #define PG8_MMA(ai, bj, At, Bt) do { __builtin_amdgcn_s_setprio(1); _Pragma("unroll") for (int m = 0; m < 4; ++m) _Pragma("unroll") for (int n = 0; n < 2; ++n) _Pragma("unroll") for (int k = 0; k < 2; ++k) \
;         acc[ai][bj][m][n] = __builtin_amdgcn_mfma_f32_16x16x32_bf16(Bt[n][k], At[m][k], acc[ai][bj][m][n], 0, 0, 0); __builtin_amdgcn_s_setprio(0); } while (0)
; #define PG8_WAIT_V(n) asm volatile("s_waitcnt vmcnt(" #n ")" ::: "memory")
; #define PG8_WAIT_L(n) asm volatile("s_waitcnt lgkmcnt(" #n ")" ::: "memory")
; #define PG8_BAR __builtin_amdgcn_s_barrier()
; #define PG8_SCHED __builtin_amdgcn_sched_barrier(0)
; template <class Epi, class Sched = StaticOrder, class EpiSub = NoSub, bool FAST = false>
; __device__ __forceinline__ void gemm_phase(LAS unsigned char* lds, const Gemm g, const Sched& S, const Epi& E, const EpiSub& ES = EpiSub()) {
;     ...
;             PG8_WAIT_V(8); PG8_WAIT_L(0); PG8_BAR; PG8_MMA(0, 0, At, B0); PG8_MMA(0, 1, At, B1); PG8_BAR; PG8_SCHED;
;             PG8_LDA(At, 0, 1); PG8_STAGE(PG8_SB(0, 0), b2, voffB); PG8_STAGE(PG8_SB(0, 1), b2 + hstepB, voffB); PG8_STAGE(PG8_SA(0, 0), a2, voffA);
;             PG8_WAIT_V(8); PG8_WAIT_L(0); PG8_BAR; PG8_MMA(1, 0, At, B0); PG8_MMA(1, 1, At, B1); PG8_BAR; PG8_SCHED;
;             PG8_LDB(B0, 1, 0); PG8_LDB(B1, 1, 1); PG8_SCHED; PG8_LDA(At, 1, 0); PG8_STAGE(PG8_SA(0, 1), a2 + hstepA, voffA);
;             PG8_WAIT_V(8); PG8_WAIT_L(0); PG8_BAR; PG8_MMA(0, 0, At, B0); PG8_MMA(0, 1, At, B1); PG8_BAR; PG8_SCHED;
	v_mfma_f32_16x16x32_bf16 v[60:63], v[100:103], v[174:177], 0
	v_mfma_f32_16x16x32_bf16 v[56:59], v[124:127], v[174:177], 0
	v_mfma_f32_16x16x32_bf16 v[44:47], v[100:103], v[194:197], 0
	v_mfma_f32_16x16x32_bf16 v[40:43], v[124:127], v[194:197], 0
	v_mfma_f32_16x16x32_bf16 v[28:31], v[100:103], v[202:205], 0
	v_mfma_f32_16x16x32_bf16 v[24:27], v[124:127], v[202:205], 0
	v_mfma_f32_16x16x32_bf16 v[12:15], v[100:103], v[210:213], 0
	v_mfma_f32_16x16x32_bf16 v[8:11], v[124:127], v[210:213], 0
	v_mfma_f32_16x16x32_bf16 v[60:63], v[112:115], v[178:181], v[60:63]
	v_mfma_f32_16x16x32_bf16 v[56:59], v[136:139], v[178:181], v[56:59]
	v_mfma_f32_16x16x32_bf16 v[44:47], v[112:115], v[198:201], v[44:47]
	v_mfma_f32_16x16x32_bf16 v[40:43], v[136:139], v[198:201], v[40:43]
	v_mfma_f32_16x16x32_bf16 v[28:31], v[112:115], v[206:209], v[28:31]
	v_mfma_f32_16x16x32_bf16 v[24:27], v[136:139], v[206:209], v[24:27]
	v_mfma_f32_16x16x32_bf16 v[12:15], v[112:115], v[214:217], v[12:15]
	v_mfma_f32_16x16x32_bf16 v[8:11], v[136:139], v[214:217], v[8:11]
	v_mfma_f32_16x16x32_bf16 v[52:55], v[144:147], v[174:177], 0
	v_mfma_f32_16x16x32_bf16 v[48:51], v[152:155], v[174:177], 0
	v_mfma_f32_16x16x32_bf16 v[36:39], v[144:147], v[194:197], 0
	v_mfma_f32_16x16x32_bf16 v[32:35], v[152:155], v[194:197], 0
	v_mfma_f32_16x16x32_bf16 v[20:23], v[144:147], v[202:205], 0
	v_mfma_f32_16x16x32_bf16 v[16:19], v[152:155], v[202:205], 0
	v_mfma_f32_16x16x32_bf16 v[4:7], v[144:147], v[210:213], 0
	v_mfma_f32_16x16x32_bf16 v[0:3], v[152:155], v[210:213], 0
	v_mfma_f32_16x16x32_bf16 v[52:55], v[148:151], v[178:181], v[52:55]
	v_mfma_f32_16x16x32_bf16 v[48:51], v[170:173], v[178:181], v[48:51]
	v_mfma_f32_16x16x32_bf16 v[36:39], v[148:151], v[198:201], v[36:39]
	v_mfma_f32_16x16x32_bf16 v[32:35], v[170:173], v[198:201], v[32:35]
	v_mfma_f32_16x16x32_bf16 v[20:23], v[148:151], v[206:209], v[20:23]
	v_mfma_f32_16x16x32_bf16 v[16:19], v[170:173], v[206:209], v[16:19]
	v_mfma_f32_16x16x32_bf16 v[4:7], v[148:151], v[214:217], v[4:7]
	v_mfma_f32_16x16x32_bf16 v[0:3], v[170:173], v[214:217], v[0:3]
	s_barrier
	s_add_i32 s50, 0, 0x18000
	s_add_i32 s70, 0, 0x1c000
	v_add_u32_e32 v136, s50, v183
	v_add_u32_e32 v170, s70, v183
	ds_read_b128 v[100:103], v136
	ds_read_b128 v[112:115], v136 offset:1024
	ds_read_b128 v[124:127], v136 offset:2048
	ds_read_b128 v[136:139], v136 offset:3072
	ds_read_b128 v[144:147], v170
	ds_read_b128 v[148:151], v170 offset:1024
	ds_read_b128 v[152:155], v170 offset:2048
	ds_read_b128 v[170:173], v170 offset:3072
	s_add_u32 s52, s52, 0x40000
	s_addc_u32 s53, s53, 0
	s_mov_b32 m0, s57
	v_lshl_add_u64 v[224:225], s[52:53], 0, v[156:157]
	ds_read_b128 v[174:177], v188 offset:32768
	ds_read_b128 v[178:181], v188 offset:33792
	ds_read_b128 v[194:197], v188 offset:34816
	ds_read_b128 v[198:201], v188 offset:35840
	ds_read_b128 v[202:205], v188 offset:36864
	ds_read_b128 v[206:209], v188 offset:37888
	ds_read_b128 v[210:213], v188 offset:38912
	ds_read_b128 v[214:217], v188 offset:39936
	global_load_lds_dwordx4 v[224:225], off
	v_lshl_add_u64 v[224:225], s[52:53], 0, v[160:161]
	s_mov_b32 m0, s58
	s_nop 0
	global_load_lds_dwordx4 v[224:225], off
	s_waitcnt vmcnt(8)
	s_waitcnt lgkmcnt(0)
	s_barrier
	v_mfma_f32_16x16x32_bf16 v[140:143], v[100:103], v[174:177], v[140:143]
	v_mfma_f32_16x16x32_bf16 v[132:135], v[124:127], v[174:177], v[132:135]
	v_mfma_f32_16x16x32_bf16 v[116:119], v[100:103], v[194:197], v[116:119]
	v_mfma_f32_16x16x32_bf16 v[108:111], v[124:127], v[194:197], v[108:111]
	v_mfma_f32_16x16x32_bf16 v[92:95], v[100:103], v[202:205], v[92:95]
	v_mfma_f32_16x16x32_bf16 v[88:91], v[124:127], v[202:205], v[88:91]
	v_mfma_f32_16x16x32_bf16 v[76:79], v[100:103], v[210:213], v[76:79]
	v_mfma_f32_16x16x32_bf16 v[72:75], v[124:127], v[210:213], v[72:75]
	v_mfma_f32_16x16x32_bf16 v[140:143], v[112:115], v[178:181], v[140:143]
	v_mfma_f32_16x16x32_bf16 v[132:135], v[136:139], v[178:181], v[132:135]
	v_mfma_f32_16x16x32_bf16 v[116:119], v[112:115], v[198:201], v[116:119]
	v_mfma_f32_16x16x32_bf16 v[108:111], v[136:139], v[198:201], v[108:111]
	v_mfma_f32_16x16x32_bf16 v[92:95], v[112:115], v[206:209], v[92:95]
	v_mfma_f32_16x16x32_bf16 v[88:91], v[136:139], v[206:209], v[88:91]
	v_mfma_f32_16x16x32_bf16 v[76:79], v[112:115], v[214:217], v[76:79]
	v_mfma_f32_16x16x32_bf16 v[72:75], v[136:139], v[214:217], v[72:75]
	v_mfma_f32_16x16x32_bf16 v[128:131], v[144:147], v[174:177], v[128:131]
	v_mfma_f32_16x16x32_bf16 v[120:123], v[152:155], v[174:177], v[120:123]
	v_mfma_f32_16x16x32_bf16 v[104:107], v[144:147], v[194:197], v[104:107]
	v_mfma_f32_16x16x32_bf16 v[96:99], v[152:155], v[194:197], v[96:99]
	v_mfma_f32_16x16x32_bf16 v[84:87], v[144:147], v[202:205], v[84:87]
	v_mfma_f32_16x16x32_bf16 v[80:83], v[152:155], v[202:205], v[80:83]
	v_mfma_f32_16x16x32_bf16 v[68:71], v[144:147], v[210:213], v[68:71]
	v_mfma_f32_16x16x32_bf16 v[64:67], v[152:155], v[210:213], v[64:67]
	v_mfma_f32_16x16x32_bf16 v[128:131], v[148:151], v[178:181], v[128:131]
	v_mfma_f32_16x16x32_bf16 v[120:123], v[170:173], v[178:181], v[120:123]
	v_mfma_f32_16x16x32_bf16 v[104:107], v[148:151], v[198:201], v[104:107]
	v_mfma_f32_16x16x32_bf16 v[96:99], v[170:173], v[198:201], v[96:99]
	v_mfma_f32_16x16x32_bf16 v[84:87], v[148:151], v[206:209], v[84:87]
	v_mfma_f32_16x16x32_bf16 v[80:83], v[170:173], v[206:209], v[80:83]
	v_mfma_f32_16x16x32_bf16 v[68:71], v[148:151], v[214:217], v[68:71]
	v_mfma_f32_16x16x32_bf16 v[64:67], v[170:173], v[214:217], v[64:67]
	s_barrier
; #define PG8_STAGE(bufoff, gbase, voff) do { _Pragma("unroll") for (int _i = 0; _i < 2; ++_i) \
;         __builtin_amdgcn_global_load_lds((const unsigned*)((const char*)(gbase) + (voff)[_i]), (LAS unsigned*)(lds + (bufoff) + ldsw + _i * 8192), 16, 0, 0); } while (0)
; #define PG8_LDA(dst, b, h) do { _Pragma("unroll") for (int m = 0; m < 4; ++m) _Pragma("unroll") for (int k = 0; k < 2; ++k) dst[m][k] = *(const LAS bf16x8*)(lds + PG8_SA(b, h) + aoff + m * 2048 + k * 1024); } while (0)
; #define PG8_MMA(ai, bj, At, Bt) do { __builtin_amdgcn_s_setprio(1); _Pragma("unroll") for (int m = 0; m < 4; ++m) _Pragma("unroll") for (int n = 0; n < 2; ++n) _Pragma("unroll") for (int k = 0; k < 2; ++k) \
;         acc[ai][bj][m][n] = __builtin_amdgcn_mfma_f32_16x16x32_bf16(Bt[n][k], At[m][k], acc[ai][bj][m][n], 0, 0, 0); __builtin_amdgcn_s_setprio(0); } while (0)
; #define PG8_WAIT_V(n) asm volatile("s_waitcnt vmcnt(" #n ")" ::: "memory")
; #define PG8_WAIT_L(n) asm volatile("s_waitcnt lgkmcnt(" #n ")" ::: "memory")
; #define PG8_BAR __builtin_amdgcn_s_barrier()
; #define PG8_SCHED __builtin_amdgcn_sched_barrier(0)
; template <class Epi, class Sched = StaticOrder, class EpiSub = NoSub, bool FAST = false>
; __device__ __forceinline__ void gemm_phase(LAS unsigned char* lds, const Gemm g, const Sched& S, const Epi& E, const EpiSub& ES = EpiSub()) {
;     ...
;             PG8_WAIT_V(8); PG8_WAIT_L(0); PG8_BAR; PG8_MMA(0, 0, At, B0); PG8_MMA(0, 1, At, B1); PG8_BAR; PG8_SCHED;
;             PG8_LDA(At, 1, 1); PG8_STAGE(PG8_SB(1, 0), b3, voffB); PG8_STAGE(PG8_SB(1, 1), b3 + hstepB, voffB); PG8_STAGE(PG8_SA(1, 0), a3, voffA);
;             PG8_WAIT_V(8); PG8_WAIT_L(0); PG8_BAR; PG8_MMA(1, 0, At, B0); PG8_MMA(1, 1, At, B1); PG8_BAR; PG8_SCHED;
	s_add_i32 s50, s50, s54
	v_lshl_add_u64 v[190:191], v[190:191], 0, s[12:13]
	s_mov_b32 m0, s50
	ds_read_b128 v[174:177], v188 offset:49152
	ds_read_b128 v[178:181], v188 offset:50176
	ds_read_b128 v[194:197], v188 offset:51200
	ds_read_b128 v[198:201], v188 offset:52224
	ds_read_b128 v[202:205], v188 offset:53248
	ds_read_b128 v[206:209], v188 offset:54272
	ds_read_b128 v[210:213], v188 offset:55296
	ds_read_b128 v[214:217], v188 offset:56320
	global_load_lds_dwordx4 v[190:191], off
	s_add_i32 m0, s50, 0x2000
	s_add_u32 s42, s42, 0x40080
	v_lshl_add_u64 v[190:191], v[218:219], 0, s[12:13]
	s_addc_u32 s43, s43, 0
	s_add_i32 s50, s70, s54
	global_load_lds_dwordx4 v[190:191], off
	v_lshl_add_u64 v[190:191], s[42:43], 0, v[158:159]
	s_mov_b32 m0, s50
	s_nop 0
	global_load_lds_dwordx4 v[190:191], off
	v_lshl_add_u64 v[190:191], s[42:43], 0, v[162:163]
	s_add_i32 m0, s50, 0x2000
	s_nop 0
	global_load_lds_dwordx4 v[190:191], off
	v_lshl_add_u64 v[190:191], v[220:221], 0, s[12:13]
	s_mov_b32 m0, s69
	s_nop 0
	global_load_lds_dwordx4 v[190:191], off
	v_lshl_add_u64 v[190:191], v[222:223], 0, s[12:13]
	s_mov_b32 m0, s74
	s_nop 0
	global_load_lds_dwordx4 v[190:191], off
	s_waitcnt vmcnt(8)
	s_waitcnt lgkmcnt(0)
	s_barrier
	v_mfma_f32_16x16x32_bf16 v[60:63], v[100:103], v[174:177], v[60:63]
	v_mfma_f32_16x16x32_bf16 v[56:59], v[124:127], v[174:177], v[56:59]
	v_mfma_f32_16x16x32_bf16 v[44:47], v[100:103], v[194:197], v[44:47]
	v_mfma_f32_16x16x32_bf16 v[40:43], v[124:127], v[194:197], v[40:43]
	v_mfma_f32_16x16x32_bf16 v[28:31], v[100:103], v[202:205], v[28:31]
	v_mfma_f32_16x16x32_bf16 v[24:27], v[124:127], v[202:205], v[24:27]
	v_mfma_f32_16x16x32_bf16 v[12:15], v[100:103], v[210:213], v[12:15]
	v_mfma_f32_16x16x32_bf16 v[8:11], v[124:127], v[210:213], v[8:11]
	v_mfma_f32_16x16x32_bf16 v[60:63], v[112:115], v[178:181], v[60:63]
	v_mfma_f32_16x16x32_bf16 v[56:59], v[136:139], v[178:181], v[56:59]
	v_mfma_f32_16x16x32_bf16 v[44:47], v[112:115], v[198:201], v[44:47]
	v_mfma_f32_16x16x32_bf16 v[40:43], v[136:139], v[198:201], v[40:43]
	v_mfma_f32_16x16x32_bf16 v[28:31], v[112:115], v[206:209], v[28:31]
	v_mfma_f32_16x16x32_bf16 v[24:27], v[136:139], v[206:209], v[24:27]
	v_mfma_f32_16x16x32_bf16 v[12:15], v[112:115], v[214:217], v[12:15]
	v_mfma_f32_16x16x32_bf16 v[8:11], v[136:139], v[214:217], v[8:11]
	v_mfma_f32_16x16x32_bf16 v[52:55], v[144:147], v[174:177], v[52:55]
	v_mfma_f32_16x16x32_bf16 v[48:51], v[152:155], v[174:177], v[48:51]
	v_mfma_f32_16x16x32_bf16 v[36:39], v[144:147], v[194:197], v[36:39]
	v_mfma_f32_16x16x32_bf16 v[32:35], v[152:155], v[194:197], v[32:35]
	v_mfma_f32_16x16x32_bf16 v[20:23], v[144:147], v[202:205], v[20:23]
	v_mfma_f32_16x16x32_bf16 v[16:19], v[152:155], v[202:205], v[16:19]
	v_mfma_f32_16x16x32_bf16 v[4:7], v[144:147], v[210:213], v[4:7]
	v_mfma_f32_16x16x32_bf16 v[0:3], v[152:155], v[210:213], v[0:3]
	v_mfma_f32_16x16x32_bf16 v[52:55], v[148:151], v[178:181], v[52:55]
	v_mfma_f32_16x16x32_bf16 v[48:51], v[170:173], v[178:181], v[48:51]
	v_mfma_f32_16x16x32_bf16 v[36:39], v[148:151], v[198:201], v[36:39]
	v_mfma_f32_16x16x32_bf16 v[32:35], v[170:173], v[198:201], v[32:35]
	v_mfma_f32_16x16x32_bf16 v[20:23], v[148:151], v[206:209], v[20:23]
	v_mfma_f32_16x16x32_bf16 v[16:19], v[170:173], v[206:209], v[16:19]
	v_mfma_f32_16x16x32_bf16 v[4:7], v[148:151], v[214:217], v[4:7]
	v_mfma_f32_16x16x32_bf16 v[0:3], v[170:173], v[214:217], v[0:3]
	s_barrier
	s_add_u32 s40, s40, 0x100
	s_addc_u32 s41, s41, 0
	s_add_u32 s48, s48, 0x100
	s_addc_u32 s49, s49, 0
	s_cmp_ge_u32 s51, s27
	s_mov_b32 s50, s51
	s_cbranch_scc1 .Lkpeel_600_exit

; #define PG8_STAGE(bufoff, gbase, voff) do { _Pragma("unroll") for (int _i = 0; _i < 2; ++_i) \
;         __builtin_amdgcn_global_load_lds((const unsigned*)((const char*)(gbase) + (voff)[_i]), (LAS unsigned*)(lds + (bufoff) + ldsw + _i * 8192), 16, 0, 0); } while (0)
; #define PG8_LDA(dst, b, h) do { _Pragma("unroll") for (int m = 0; m < 4; ++m) _Pragma("unroll") for (int k = 0; k < 2; ++k) dst[m][k] = *(const LAS bf16x8*)(lds + PG8_SA(b, h) + aoff + m * 2048 + k * 1024); } while (0)
; #define PG8_LDB(dst, b, h) do { _Pragma("unroll") for (int n = 0; n < 2; ++n) _Pragma("unroll") for (int k = 0; k < 2; ++k) dst[n][k] = *(const LAS bf16x8*)(lds + PG8_SB(b, h) + boff + n * 2048 + k * 1024); } while (0)
; #define PG8_MMA(ai, bj, At, Bt) do { __builtin_amdgcn_s_setprio(1); _Pragma("unroll") for (int m = 0; m < 4; ++m) _Pragma("unroll") for (int n = 0; n < 2; ++n) _Pragma("unroll") for (int k = 0; k < 2; ++k) \
;         acc[ai][bj][m][n] = __builtin_amdgcn_mfma_f32_16x16x32_bf16(Bt[n][k], At[m][k], acc[ai][bj][m][n], 0, 0, 0); __builtin_amdgcn_s_setprio(0); } while (0)
; #define PG8_BAR __builtin_amdgcn_s_barrier()
; template <class Epi, class Sched = StaticOrder, class EpiSub = NoSub, bool FAST = false>
; __device__ __forceinline__ void gemm_phase(LAS unsigned char* lds, const Gemm g, const Sched& S, const Epi& E, const EpiSub& ES = EpiSub()) {
;     ...
;         const bool has_next = S.next(ui + 1, nxt);
;         const size_t nko = (has_next && nxt.kb >= 0) ? nxt.kb * ksubB : 0;
;         const char* nA = has_next ? (const char*)g.A + (size_t)nxt.pm * tstepA + (size_t)nxt.pn * g.acs + nko : cA; const char* nB = has_next ? (const char*)g.Bt + (size_t)nxt.pn * tstepB + nko : cB;
;         const int nt = cur.kb < 0 ? ntMain : ntSub;
;         for (int t = 0; t < nt; t += 2) {
;             const bool last = (t == nt - 2);
;             const char* a1 = cA + (size_t)(t + 1) * kstep;
;             const char* a2 = last ? nA : cA + (size_t)(t + 2) * kstep; const char* b2 = last ? nB : cB + (size_t)(t + 2) * kstep;
;             const char* a3 = a2 + kstep; const char* b3 = b2 + kstep;
;             if constexpr (FAST && PG8_SP2) {
;             PG8_LDB(B0, 0, 0); PG8_LDB(B1, 0, 1); PG8_SCHED; PG8_LDA(At, 0, 0); PG8_STAGE(PG8_SA(1, 1), a1 + hstepA, voffA);
;             PG8_WAIT_V(8); PG8_WAIT_L(0); PG8_BAR; PG8_MMA(0, 0, At, B0); PG8_MMA(0, 1, At, B1); PG8_BAR; PG8_SCHED;
.LBB0_631:
	s_cmp_gt_i32 s8, -1
	s_cselect_b64 s[26:27], -1, 0
	s_and_b64 s[26:27], s[24:25], s[26:27]
	s_lshl_b64 s[28:29], s[8:9], 10
	s_and_b64 s[26:27], s[26:27], exec
	s_cselect_b32 s31, s29, 0
	s_cselect_b32 s33, s28, 0
	s_ashr_i32 s23, s22, 31
	s_lshl_b64 s[26:27], s[22:23], 20
	v_readlane_b32 s28, v254, 36
	v_readlane_b32 s29, v254, 37
	s_add_u32 s1, s28, s26
	s_addc_u32 s5, s29, s27
	s_add_u32 s26, s1, s33
	s_addc_u32 s27, s5, s31
	s_and_b64 s[28:29], s[24:25], exec
	s_cselect_b32 s1, s27, s39
	s_cselect_b32 s5, s26, s38
	s_ashr_i32 s21, s20, 31
	s_lshl_b64 s[28:29], s[20:21], 20
	s_add_u32 s21, s2, s28
	s_addc_u32 s23, s3, s29
	s_add_u32 s28, s21, s33
	s_addc_u32 s29, s23, s31
	s_and_b64 s[36:37], s[24:25], exec
	s_cselect_b32 s21, s29, s41
	s_cselect_b32 s23, s28, s40
	s_cmp_gt_i32 s0, -1
	s_cselect_b64 s[36:37], -1, 0
	s_cmp_lt_i32 s0, 0
	s_cselect_b32 s31, 32, 8
	s_add_i32 s33, s31, -2
	s_add_u32 s38, s38, 0x80080
	s_addc_u32 s39, s39, 0
	s_add_u32 s48, s40, 0x100
	s_mov_b32 s42, 0
	s_addc_u32 s49, s41, 0
	s_cmp_eq_u64 s[14:15], 0
	s_cbranch_scc0 .Lkprio_632
	s_setprio 1
.Lkprio_632:
	ds_read_b128 v[104:107], v224
	ds_read_b128 v[108:111], v224 offset:1024
	ds_read_b128 v[120:123], v224 offset:2048
	ds_read_b128 v[124:127], v224 offset:3072
	ds_read_b128 v[136:139], v225
	ds_read_b128 v[140:143], v225 offset:1024
	ds_read_b128 v[152:155], v225 offset:2048
	ds_read_b128 v[156:159], v225 offset:3072
	s_add_i32 s50, s42, 2
	s_add_u32 s40, s38, 0xfff80080
	s_addc_u32 s41, s39, -1
	s_cmp_eq_u32 s33, s42
	s_cselect_b32 s42, s5, s40
	s_cselect_b32 s43, s1, s41
	s_cselect_b32 s41, s21, s49
	s_cselect_b32 s40, s23, s48
	v_lshl_add_u64 v[208:209], s[38:39], 0, v[202:203]
	s_add_i32 m0, s53, 0xc000
	ds_read_b128 v[160:163], v226
	ds_read_b128 v[164:167], v226 offset:1024
	ds_read_b128 v[168:171], v226 offset:2048
	ds_read_b128 v[172:175], v226 offset:3072
	ds_read_b128 v[176:179], v226 offset:4096
	ds_read_b128 v[180:183], v226 offset:5120
	ds_read_b128 v[184:187], v226 offset:6144
	ds_read_b128 v[188:191], v226 offset:7168
	global_load_lds_dwordx4 v[208:209], off
	v_lshl_add_u64 v[208:209], s[38:39], 0, v[204:205]
	s_add_i32 m0, s53, 0xe000
	s_nop 0
	global_load_lds_dwordx4 v[208:209], off
	s_waitcnt vmcnt(8)
	s_waitcnt lgkmcnt(0)
	s_barrier
	v_mfma_f32_16x16x32_bf16 v[148:151], v[104:107], v[160:163], 0
	v_mfma_f32_16x16x32_bf16 v[144:147], v[120:123], v[160:163], 0
	v_mfma_f32_16x16x32_bf16 v[116:119], v[104:107], v[168:171], 0
	v_mfma_f32_16x16x32_bf16 v[112:115], v[120:123], v[168:171], 0
	v_mfma_f32_16x16x32_bf16 v[92:95], v[104:107], v[176:179], 0
	v_mfma_f32_16x16x32_bf16 v[88:91], v[120:123], v[176:179], 0
	v_mfma_f32_16x16x32_bf16 v[76:79], v[104:107], v[184:187], 0
	v_mfma_f32_16x16x32_bf16 v[72:75], v[120:123], v[184:187], 0
	v_mfma_f32_16x16x32_bf16 v[148:151], v[108:111], v[164:167], v[148:151]
	v_mfma_f32_16x16x32_bf16 v[144:147], v[124:127], v[164:167], v[144:147]
	v_mfma_f32_16x16x32_bf16 v[116:119], v[108:111], v[172:175], v[116:119]
	v_mfma_f32_16x16x32_bf16 v[112:115], v[124:127], v[172:175], v[112:115]
	v_mfma_f32_16x16x32_bf16 v[92:95], v[108:111], v[180:183], v[92:95]
	v_mfma_f32_16x16x32_bf16 v[88:91], v[124:127], v[180:183], v[88:91]
	v_mfma_f32_16x16x32_bf16 v[76:79], v[108:111], v[188:191], v[76:79]
	v_mfma_f32_16x16x32_bf16 v[72:75], v[124:127], v[188:191], v[72:75]
	v_mfma_f32_16x16x32_bf16 v[132:135], v[136:139], v[160:163], 0
	v_mfma_f32_16x16x32_bf16 v[128:131], v[152:155], v[160:163], 0
	v_mfma_f32_16x16x32_bf16 v[100:103], v[136:139], v[168:171], 0
	v_mfma_f32_16x16x32_bf16 v[96:99], v[152:155], v[168:171], 0
	v_mfma_f32_16x16x32_bf16 v[84:87], v[136:139], v[176:179], 0
	v_mfma_f32_16x16x32_bf16 v[80:83], v[152:155], v[176:179], 0
	v_mfma_f32_16x16x32_bf16 v[68:71], v[136:139], v[184:187], 0
	v_mfma_f32_16x16x32_bf16 v[64:67], v[152:155], v[184:187], 0
	v_mfma_f32_16x16x32_bf16 v[132:135], v[140:143], v[164:167], v[132:135]
	v_mfma_f32_16x16x32_bf16 v[128:131], v[156:159], v[164:167], v[128:131]
	v_mfma_f32_16x16x32_bf16 v[100:103], v[140:143], v[172:175], v[100:103]
	v_mfma_f32_16x16x32_bf16 v[96:99], v[156:159], v[172:175], v[96:99]
	v_mfma_f32_16x16x32_bf16 v[84:87], v[140:143], v[180:183], v[84:87]
	v_mfma_f32_16x16x32_bf16 v[80:83], v[156:159], v[180:183], v[80:83]
	v_mfma_f32_16x16x32_bf16 v[68:71], v[140:143], v[188:191], v[68:71]
	v_mfma_f32_16x16x32_bf16 v[64:67], v[156:159], v[188:191], v[64:67]
	s_barrier
	s_add_i32 s51, s75, s52
	v_lshl_add_u64 v[208:209], s[40:41], 0, v[196:197]
	s_mov_b32 m0, s51
	ds_read_b128 v[160:163], v226 offset:16384
	ds_read_b128 v[164:167], v226 offset:17408
	ds_read_b128 v[168:171], v226 offset:18432
	ds_read_b128 v[172:175], v226 offset:19456
	ds_read_b128 v[176:179], v226 offset:20480
	ds_read_b128 v[180:183], v226 offset:21504
	ds_read_b128 v[184:187], v226 offset:22528
	ds_read_b128 v[188:191], v226 offset:23552
	global_load_lds_dwordx4 v[208:209], off
	s_add_i32 m0, s51, 0x2000
	s_add_u32 s70, s40, 0x80000
	v_lshl_add_u64 v[210:211], s[40:41], 0, v[200:201]
	s_addc_u32 s71, s41, 0
	s_add_i32 s51, s78, s52
	global_load_lds_dwordx4 v[210:211], off
	v_lshl_add_u64 v[212:213], s[70:71], 0, v[196:197]
	s_mov_b32 m0, s51
	v_lshl_add_u64 v[214:215], s[42:43], 0, v[198:199]
	global_load_lds_dwordx4 v[212:213], off
	v_lshl_add_u64 v[212:213], s[70:71], 0, v[200:201]
	s_add_i32 m0, s51, 0x2000
	s_nop 0
	global_load_lds_dwordx4 v[212:213], off
	v_lshl_add_u64 v[212:213], s[42:43], 0, v[194:195]
	s_mov_b32 m0, s53
	s_nop 0
	global_load_lds_dwordx4 v[212:213], off
	s_mov_b32 m0, s54
	s_nop 0
	global_load_lds_dwordx4 v[214:215], off
	s_waitcnt vmcnt(8)
	s_waitcnt lgkmcnt(0)
	s_barrier
; #define PG8_STAGE(bufoff, gbase, voff) do { _Pragma("unroll") for (int _i = 0; _i < 2; ++_i) \
;         __builtin_amdgcn_global_load_lds((const unsigned*)((const char*)(gbase) + (voff)[_i]), (LAS unsigned*)(lds + (bufoff) + ldsw + _i * 8192), 16, 0, 0); } while (0)
; #define PG8_LDA(dst, b, h) do { _Pragma("unroll") for (int m = 0; m < 4; ++m) _Pragma("unroll") for (int k = 0; k < 2; ++k) dst[m][k] = *(const LAS bf16x8*)(lds + PG8_SA(b, h) + aoff + m * 2048 + k * 1024); } while (0)
; #define PG8_LDB(dst, b, h) do { _Pragma("unroll") for (int n = 0; n < 2; ++n) _Pragma("unroll") for (int k = 0; k < 2; ++k) dst[n][k] = *(const LAS bf16x8*)(lds + PG8_SB(b, h) + boff + n * 2048 + k * 1024); } while (0)
; #define PG8_MMA(ai, bj, At, Bt) do { __builtin_amdgcn_s_setprio(1); _Pragma("unroll") for (int m = 0; m < 4; ++m) _Pragma("unroll") for (int n = 0; n < 2; ++n) _Pragma("unroll") for (int k = 0; k < 2; ++k) \
;         acc[ai][bj][m][n] = __builtin_amdgcn_mfma_f32_16x16x32_bf16(Bt[n][k], At[m][k], acc[ai][bj][m][n], 0, 0, 0); __builtin_amdgcn_s_setprio(0); } while (0)
; #define PG8_WAIT_V(n) asm volatile("s_waitcnt vmcnt(" #n ")" ::: "memory")
; #define PG8_WAIT_L(n) asm volatile("s_waitcnt lgkmcnt(" #n ")" ::: "memory")
; #define PG8_BAR __builtin_amdgcn_s_barrier()
; #define PG8_SCHED __builtin_amdgcn_sched_barrier(0)
; template <class Epi, class Sched = StaticOrder, class EpiSub = NoSub, bool FAST = false>
; __device__ __forceinline__ void gemm_phase(LAS unsigned char* lds, const Gemm g, const Sched& S, const Epi& E, const EpiSub& ES = EpiSub()) {
;     ...
;             PG8_WAIT_V(8); PG8_WAIT_L(0); PG8_BAR; PG8_MMA(0, 0, At, B0); PG8_MMA(0, 1, At, B1); PG8_BAR; PG8_SCHED;
;             PG8_LDA(At, 0, 1); PG8_STAGE(PG8_SB(0, 0), b2, voffB); PG8_STAGE(PG8_SB(0, 1), b2 + hstepB, voffB); PG8_STAGE(PG8_SA(0, 0), a2, voffA);
;             PG8_WAIT_V(8); PG8_WAIT_L(0); PG8_BAR; PG8_MMA(1, 0, At, B0); PG8_MMA(1, 1, At, B1); PG8_BAR; PG8_SCHED;
;             PG8_LDB(B0, 1, 0); PG8_LDB(B1, 1, 1); PG8_SCHED; PG8_LDA(At, 1, 0); PG8_STAGE(PG8_SA(0, 1), a2 + hstepA, voffA);
;             PG8_WAIT_V(8); PG8_WAIT_L(0); PG8_BAR; PG8_MMA(0, 0, At, B0); PG8_MMA(0, 1, At, B1); PG8_BAR; PG8_SCHED;
	v_mfma_f32_16x16x32_bf16 v[60:63], v[104:107], v[160:163], 0
	v_mfma_f32_16x16x32_bf16 v[56:59], v[120:123], v[160:163], 0
	v_mfma_f32_16x16x32_bf16 v[44:47], v[104:107], v[168:171], 0
	v_mfma_f32_16x16x32_bf16 v[40:43], v[120:123], v[168:171], 0
	v_mfma_f32_16x16x32_bf16 v[28:31], v[104:107], v[176:179], 0
	v_mfma_f32_16x16x32_bf16 v[24:27], v[120:123], v[176:179], 0
	v_mfma_f32_16x16x32_bf16 v[12:15], v[104:107], v[184:187], 0
	v_mfma_f32_16x16x32_bf16 v[8:11], v[120:123], v[184:187], 0
	v_mfma_f32_16x16x32_bf16 v[60:63], v[108:111], v[164:167], v[60:63]
	v_mfma_f32_16x16x32_bf16 v[56:59], v[124:127], v[164:167], v[56:59]
	v_mfma_f32_16x16x32_bf16 v[44:47], v[108:111], v[172:175], v[44:47]
	v_mfma_f32_16x16x32_bf16 v[40:43], v[124:127], v[172:175], v[40:43]
	v_mfma_f32_16x16x32_bf16 v[28:31], v[108:111], v[180:183], v[28:31]
	v_mfma_f32_16x16x32_bf16 v[24:27], v[124:127], v[180:183], v[24:27]
	v_mfma_f32_16x16x32_bf16 v[12:15], v[108:111], v[188:191], v[12:15]
	v_mfma_f32_16x16x32_bf16 v[8:11], v[124:127], v[188:191], v[8:11]
	v_mfma_f32_16x16x32_bf16 v[52:55], v[136:139], v[160:163], 0
	v_mfma_f32_16x16x32_bf16 v[48:51], v[152:155], v[160:163], 0
	v_mfma_f32_16x16x32_bf16 v[36:39], v[136:139], v[168:171], 0
	v_mfma_f32_16x16x32_bf16 v[32:35], v[152:155], v[168:171], 0
	v_mfma_f32_16x16x32_bf16 v[20:23], v[136:139], v[176:179], 0
	v_mfma_f32_16x16x32_bf16 v[16:19], v[152:155], v[176:179], 0
	v_mfma_f32_16x16x32_bf16 v[4:7], v[136:139], v[184:187], 0
	v_mfma_f32_16x16x32_bf16 v[0:3], v[152:155], v[184:187], 0
	v_mfma_f32_16x16x32_bf16 v[52:55], v[140:143], v[164:167], v[52:55]
	v_mfma_f32_16x16x32_bf16 v[48:51], v[156:159], v[164:167], v[48:51]
	v_mfma_f32_16x16x32_bf16 v[36:39], v[140:143], v[172:175], v[36:39]
	v_mfma_f32_16x16x32_bf16 v[32:35], v[156:159], v[172:175], v[32:35]
	v_mfma_f32_16x16x32_bf16 v[20:23], v[140:143], v[180:183], v[20:23]
	v_mfma_f32_16x16x32_bf16 v[16:19], v[156:159], v[180:183], v[16:19]
	v_mfma_f32_16x16x32_bf16 v[4:7], v[140:143], v[188:191], v[4:7]
	v_mfma_f32_16x16x32_bf16 v[0:3], v[156:159], v[188:191], v[0:3]
	s_barrier
	s_add_i32 s51, 0, 0x18000
	s_add_i32 s70, 0, 0x1c000
	v_add_u32_e32 v124, s51, v221
	v_add_u32_e32 v156, s70, v221
	ds_read_b128 v[104:107], v124
	ds_read_b128 v[108:111], v124 offset:1024
	ds_read_b128 v[120:123], v124 offset:2048
	ds_read_b128 v[124:127], v124 offset:3072
	ds_read_b128 v[136:139], v156
	ds_read_b128 v[140:143], v156 offset:1024
	ds_read_b128 v[152:155], v156 offset:2048
	ds_read_b128 v[156:159], v156 offset:3072
	s_add_u32 s42, s42, 0x80000
	s_addc_u32 s43, s43, 0
	s_mov_b32 m0, s55
	v_lshl_add_u64 v[216:217], s[42:43], 0, v[194:195]
	ds_read_b128 v[160:163], v226 offset:32768
	ds_read_b128 v[164:167], v226 offset:33792
	ds_read_b128 v[168:171], v226 offset:34816
	ds_read_b128 v[172:175], v226 offset:35840
	ds_read_b128 v[176:179], v226 offset:36864
	ds_read_b128 v[180:183], v226 offset:37888
	ds_read_b128 v[184:187], v226 offset:38912
	ds_read_b128 v[188:191], v226 offset:39936
	global_load_lds_dwordx4 v[216:217], off
	v_lshl_add_u64 v[216:217], s[42:43], 0, v[198:199]
	s_mov_b32 m0, s56
	s_nop 0
	global_load_lds_dwordx4 v[216:217], off
	s_waitcnt vmcnt(8)
	s_waitcnt lgkmcnt(0)
	s_barrier
	v_mfma_f32_16x16x32_bf16 v[148:151], v[104:107], v[160:163], v[148:151]
	v_mfma_f32_16x16x32_bf16 v[144:147], v[120:123], v[160:163], v[144:147]
	v_mfma_f32_16x16x32_bf16 v[116:119], v[104:107], v[168:171], v[116:119]
	v_mfma_f32_16x16x32_bf16 v[112:115], v[120:123], v[168:171], v[112:115]
	v_mfma_f32_16x16x32_bf16 v[92:95], v[104:107], v[176:179], v[92:95]
	v_mfma_f32_16x16x32_bf16 v[88:91], v[120:123], v[176:179], v[88:91]
	v_mfma_f32_16x16x32_bf16 v[76:79], v[104:107], v[184:187], v[76:79]
	v_mfma_f32_16x16x32_bf16 v[72:75], v[120:123], v[184:187], v[72:75]
	v_mfma_f32_16x16x32_bf16 v[148:151], v[108:111], v[164:167], v[148:151]
	v_mfma_f32_16x16x32_bf16 v[144:147], v[124:127], v[164:167], v[144:147]
	v_mfma_f32_16x16x32_bf16 v[116:119], v[108:111], v[172:175], v[116:119]
	v_mfma_f32_16x16x32_bf16 v[112:115], v[124:127], v[172:175], v[112:115]
	v_mfma_f32_16x16x32_bf16 v[92:95], v[108:111], v[180:183], v[92:95]
	v_mfma_f32_16x16x32_bf16 v[88:91], v[124:127], v[180:183], v[88:91]
	v_mfma_f32_16x16x32_bf16 v[76:79], v[108:111], v[188:191], v[76:79]
	v_mfma_f32_16x16x32_bf16 v[72:75], v[124:127], v[188:191], v[72:75]
	v_mfma_f32_16x16x32_bf16 v[132:135], v[136:139], v[160:163], v[132:135]
	v_mfma_f32_16x16x32_bf16 v[128:131], v[152:155], v[160:163], v[128:131]
	v_mfma_f32_16x16x32_bf16 v[100:103], v[136:139], v[168:171], v[100:103]
	v_mfma_f32_16x16x32_bf16 v[96:99], v[152:155], v[168:171], v[96:99]
	v_mfma_f32_16x16x32_bf16 v[84:87], v[136:139], v[176:179], v[84:87]
	v_mfma_f32_16x16x32_bf16 v[80:83], v[152:155], v[176:179], v[80:83]
	v_mfma_f32_16x16x32_bf16 v[68:71], v[136:139], v[184:187], v[68:71]
	v_mfma_f32_16x16x32_bf16 v[64:67], v[152:155], v[184:187], v[64:67]
	v_mfma_f32_16x16x32_bf16 v[132:135], v[140:143], v[164:167], v[132:135]
	v_mfma_f32_16x16x32_bf16 v[128:131], v[156:159], v[164:167], v[128:131]
	v_mfma_f32_16x16x32_bf16 v[100:103], v[140:143], v[172:175], v[100:103]
	v_mfma_f32_16x16x32_bf16 v[96:99], v[156:159], v[172:175], v[96:99]
	v_mfma_f32_16x16x32_bf16 v[84:87], v[140:143], v[180:183], v[84:87]
	v_mfma_f32_16x16x32_bf16 v[80:83], v[156:159], v[180:183], v[80:83]
	v_mfma_f32_16x16x32_bf16 v[68:71], v[140:143], v[188:191], v[68:71]
	v_mfma_f32_16x16x32_bf16 v[64:67], v[156:159], v[188:191], v[64:67]
	s_barrier
; #define PG8_STAGE(bufoff, gbase, voff) do { _Pragma("unroll") for (int _i = 0; _i < 2; ++_i) \
;         __builtin_amdgcn_global_load_lds((const unsigned*)((const char*)(gbase) + (voff)[_i]), (LAS unsigned*)(lds + (bufoff) + ldsw + _i * 8192), 16, 0, 0); } while (0)
; #define PG8_LDA(dst, b, h) do { _Pragma("unroll") for (int m = 0; m < 4; ++m) _Pragma("unroll") for (int k = 0; k < 2; ++k) dst[m][k] = *(const LAS bf16x8*)(lds + PG8_SA(b, h) + aoff + m * 2048 + k * 1024); } while (0)
; #define PG8_MMA(ai, bj, At, Bt) do { __builtin_amdgcn_s_setprio(1); _Pragma("unroll") for (int m = 0; m < 4; ++m) _Pragma("unroll") for (int n = 0; n < 2; ++n) _Pragma("unroll") for (int k = 0; k < 2; ++k) \
;         acc[ai][bj][m][n] = __builtin_amdgcn_mfma_f32_16x16x32_bf16(Bt[n][k], At[m][k], acc[ai][bj][m][n], 0, 0, 0); __builtin_amdgcn_s_setprio(0); } while (0)
; #define PG8_WAIT_V(n) asm volatile("s_waitcnt vmcnt(" #n ")" ::: "memory")
; #define PG8_WAIT_L(n) asm volatile("s_waitcnt lgkmcnt(" #n ")" ::: "memory")
; #define PG8_BAR __builtin_amdgcn_s_barrier()
; #define PG8_SCHED __builtin_amdgcn_sched_barrier(0)
; template <class Epi, class Sched = StaticOrder, class EpiSub = NoSub, bool FAST = false>
; __device__ __forceinline__ void gemm_phase(LAS unsigned char* lds, const Gemm g, const Sched& S, const Epi& E, const EpiSub& ES = EpiSub()) {
;     ...
;             PG8_WAIT_V(8); PG8_WAIT_L(0); PG8_BAR; PG8_MMA(0, 0, At, B0); PG8_MMA(0, 1, At, B1); PG8_BAR; PG8_SCHED;
;             PG8_LDA(At, 1, 1); PG8_STAGE(PG8_SB(1, 0), b3, voffB); PG8_STAGE(PG8_SB(1, 1), b3 + hstepB, voffB); PG8_STAGE(PG8_SA(1, 0), a3, voffA);
;             PG8_WAIT_V(8); PG8_WAIT_L(0); PG8_BAR; PG8_MMA(1, 0, At, B0); PG8_MMA(1, 1, At, B1); PG8_BAR; PG8_SCHED;
	s_add_i32 s42, s51, s52
	v_lshl_add_u64 v[208:209], v[208:209], 0, s[12:13]
	s_mov_b32 m0, s42
	ds_read_b128 v[160:163], v226 offset:49152
	ds_read_b128 v[164:167], v226 offset:50176
	ds_read_b128 v[168:171], v226 offset:51200
	ds_read_b128 v[172:175], v226 offset:52224
	ds_read_b128 v[176:179], v226 offset:53248
	ds_read_b128 v[180:183], v226 offset:54272
	ds_read_b128 v[184:187], v226 offset:55296
	ds_read_b128 v[188:191], v226 offset:56320
	global_load_lds_dwordx4 v[208:209], off
	s_add_i32 m0, s42, 0x2000
	s_add_u32 s40, s40, 0x80080
	v_lshl_add_u64 v[208:209], v[210:211], 0, s[12:13]
	s_addc_u32 s41, s41, 0
	s_add_i32 s42, s70, s52
	global_load_lds_dwordx4 v[208:209], off
	v_lshl_add_u64 v[208:209], s[40:41], 0, v[196:197]
	s_mov_b32 m0, s42
	s_nop 0
	global_load_lds_dwordx4 v[208:209], off
	v_lshl_add_u64 v[208:209], s[40:41], 0, v[200:201]
	s_add_i32 m0, s42, 0x2000
	s_nop 0
	global_load_lds_dwordx4 v[208:209], off
	v_lshl_add_u64 v[208:209], v[212:213], 0, s[12:13]
	s_mov_b32 m0, s69
	s_nop 0
	global_load_lds_dwordx4 v[208:209], off
	v_lshl_add_u64 v[208:209], v[214:215], 0, s[12:13]
	s_mov_b32 m0, s74
	s_nop 0
	global_load_lds_dwordx4 v[208:209], off
	s_waitcnt vmcnt(8)
	s_waitcnt lgkmcnt(0)
	s_barrier
	v_mfma_f32_16x16x32_bf16 v[60:63], v[104:107], v[160:163], v[60:63]
	v_mfma_f32_16x16x32_bf16 v[56:59], v[120:123], v[160:163], v[56:59]
	v_mfma_f32_16x16x32_bf16 v[44:47], v[104:107], v[168:171], v[44:47]
	v_mfma_f32_16x16x32_bf16 v[40:43], v[120:123], v[168:171], v[40:43]
	v_mfma_f32_16x16x32_bf16 v[28:31], v[104:107], v[176:179], v[28:31]
	v_mfma_f32_16x16x32_bf16 v[24:27], v[120:123], v[176:179], v[24:27]
	v_mfma_f32_16x16x32_bf16 v[12:15], v[104:107], v[184:187], v[12:15]
	v_mfma_f32_16x16x32_bf16 v[8:11], v[120:123], v[184:187], v[8:11]
	v_mfma_f32_16x16x32_bf16 v[60:63], v[108:111], v[164:167], v[60:63]
	v_mfma_f32_16x16x32_bf16 v[56:59], v[124:127], v[164:167], v[56:59]
	v_mfma_f32_16x16x32_bf16 v[44:47], v[108:111], v[172:175], v[44:47]
	v_mfma_f32_16x16x32_bf16 v[40:43], v[124:127], v[172:175], v[40:43]
	v_mfma_f32_16x16x32_bf16 v[28:31], v[108:111], v[180:183], v[28:31]
	v_mfma_f32_16x16x32_bf16 v[24:27], v[124:127], v[180:183], v[24:27]
	v_mfma_f32_16x16x32_bf16 v[12:15], v[108:111], v[188:191], v[12:15]
	v_mfma_f32_16x16x32_bf16 v[8:11], v[124:127], v[188:191], v[8:11]
	v_mfma_f32_16x16x32_bf16 v[52:55], v[136:139], v[160:163], v[52:55]
	v_mfma_f32_16x16x32_bf16 v[48:51], v[152:155], v[160:163], v[48:51]
	v_mfma_f32_16x16x32_bf16 v[36:39], v[136:139], v[168:171], v[36:39]
	v_mfma_f32_16x16x32_bf16 v[32:35], v[152:155], v[168:171], v[32:35]
	v_mfma_f32_16x16x32_bf16 v[20:23], v[136:139], v[176:179], v[20:23]
	v_mfma_f32_16x16x32_bf16 v[16:19], v[152:155], v[176:179], v[16:19]
	v_mfma_f32_16x16x32_bf16 v[4:7], v[136:139], v[184:187], v[4:7]
	v_mfma_f32_16x16x32_bf16 v[0:3], v[152:155], v[184:187], v[0:3]
	v_mfma_f32_16x16x32_bf16 v[52:55], v[140:143], v[164:167], v[52:55]
	v_mfma_f32_16x16x32_bf16 v[48:51], v[156:159], v[164:167], v[48:51]
	v_mfma_f32_16x16x32_bf16 v[36:39], v[140:143], v[172:175], v[36:39]
	v_mfma_f32_16x16x32_bf16 v[32:35], v[156:159], v[172:175], v[32:35]
	v_mfma_f32_16x16x32_bf16 v[20:23], v[140:143], v[180:183], v[20:23]
	v_mfma_f32_16x16x32_bf16 v[16:19], v[156:159], v[180:183], v[16:19]
	v_mfma_f32_16x16x32_bf16 v[4:7], v[140:143], v[188:191], v[4:7]
	v_mfma_f32_16x16x32_bf16 v[0:3], v[156:159], v[188:191], v[0:3]
	s_barrier
	s_add_u32 s38, s38, 0x100
	s_addc_u32 s39, s39, 0
	s_add_u32 s48, s48, 0x100
	s_addc_u32 s49, s49, 0
	s_cmp_ge_u32 s50, s31
	s_mov_b32 s42, s50
	s_cbranch_scc1 .Lkpeel_632_exit

; #define PG8_STAGE(bufoff, gbase, voff) do { _Pragma("unroll") for (int _i = 0; _i < 2; ++_i) \
;         __builtin_amdgcn_global_load_lds((const unsigned*)((const char*)(gbase) + (voff)[_i]), (LAS unsigned*)(lds + (bufoff) + ldsw + _i * 8192), 16, 0, 0); } while (0)
; #define PG8_LDA(dst, b, h) do { _Pragma("unroll") for (int m = 0; m < 4; ++m) _Pragma("unroll") for (int k = 0; k < 2; ++k) dst[m][k] = *(const LAS bf16x8*)(lds + PG8_SA(b, h) + aoff + m * 2048 + k * 1024); } while (0)
; #define PG8_LDB(dst, b, h) do { _Pragma("unroll") for (int n = 0; n < 2; ++n) _Pragma("unroll") for (int k = 0; k < 2; ++k) dst[n][k] = *(const LAS bf16x8*)(lds + PG8_SB(b, h) + boff + n * 2048 + k * 1024); } while (0)
; #define PG8_MMA(ai, bj, At, Bt) do { __builtin_amdgcn_s_setprio(1); _Pragma("unroll") for (int m = 0; m < 4; ++m) _Pragma("unroll") for (int n = 0; n < 2; ++n) _Pragma("unroll") for (int k = 0; k < 2; ++k) \
;         acc[ai][bj][m][n] = __builtin_amdgcn_mfma_f32_16x16x32_bf16(Bt[n][k], At[m][k], acc[ai][bj][m][n], 0, 0, 0); __builtin_amdgcn_s_setprio(0); } while (0)
; #define PG8_BAR __builtin_amdgcn_s_barrier()
; template <class Epi, class Sched = StaticOrder, class EpiSub = NoSub, bool FAST = false>
; __device__ __forceinline__ void gemm_phase(LAS unsigned char* lds, const Gemm g, const Sched& S, const Epi& E, const EpiSub& ES = EpiSub()) {
;     ...
;         const bool has_next = S.next(ui + 1, nxt);
;         const size_t nko = (has_next && nxt.kb >= 0) ? nxt.kb * ksubB : 0;
;         const char* nA = has_next ? (const char*)g.A + (size_t)nxt.pm * tstepA + (size_t)nxt.pn * g.acs + nko : cA; const char* nB = has_next ? (const char*)g.Bt + (size_t)nxt.pn * tstepB + nko : cB;
;         const int nt = cur.kb < 0 ? ntMain : ntSub;
;         for (int t = 0; t < nt; t += 2) {
;             const bool last = (t == nt - 2);
;             const char* a1 = cA + (size_t)(t + 1) * kstep;
;             const char* a2 = last ? nA : cA + (size_t)(t + 2) * kstep; const char* b2 = last ? nB : cB + (size_t)(t + 2) * kstep;
;             const char* a3 = a2 + kstep; const char* b3 = b2 + kstep;
;             if constexpr (FAST && PG8_SP2) {
;             PG8_LDB(B0, 0, 0); PG8_LDB(B1, 0, 1); PG8_SCHED; PG8_LDA(At, 0, 0); PG8_STAGE(PG8_SA(1, 1), a1 + hstepA, voffA);
;             PG8_WAIT_V(8); PG8_WAIT_L(0); PG8_BAR; PG8_MMA(0, 0, At, B0); PG8_MMA(0, 1, At, B1); PG8_BAR; PG8_SCHED;
.LBB0_768:
	s_cmp_gt_i32 s6, -1
	s_cselect_b64 s[24:25], -1, 0
	s_and_b64 s[24:25], s[22:23], s[24:25]
	s_lshl_b64 s[26:27], s[6:7], 9
	s_and_b64 s[24:25], s[24:25], exec
	s_cselect_b32 s29, s27, 0
	s_cselect_b32 s30, s26, 0
	s_ashr_i32 s21, s20, 31
	s_lshl_b64 s[24:25], s[20:21], 20
	s_add_u32 s1, s84, s24
	s_addc_u32 s5, s85, s25
	s_add_u32 s24, s1, s30
	s_addc_u32 s25, s5, s29
	s_and_b64 s[26:27], s[22:23], exec
	s_cselect_b32 s1, s25, s39
	s_cselect_b32 s5, s24, s38
	s_ashr_i32 s19, s18, 31
	s_lshl_b64 s[26:27], s[18:19], 20
	s_add_u32 s19, s2, s26
	s_addc_u32 s21, s3, s27
	s_add_u32 s26, s19, s30
	s_addc_u32 s27, s21, s29
	s_and_b64 s[30:31], s[22:23], exec
	s_cselect_b32 s19, s27, s41
	s_cselect_b32 s21, s26, s40
	s_cmp_gt_i32 s4, -1
	s_cselect_b64 s[30:31], -1, 0
	s_cmp_lt_i32 s4, 0
	s_cselect_b32 s29, 32, 4
	s_add_i32 s33, s29, -2
	s_add_u32 s38, s38, 0x80080
	s_addc_u32 s39, s39, 0
	s_add_u32 s70, s40, 0x100
	s_mov_b32 s42, 0
	s_addc_u32 s71, s41, 0
	s_cmp_eq_u64 s[14:15], 0
	s_cbranch_scc0 .Lkprio_769
	s_setprio 1
.Lkprio_769:
	ds_read_b128 v[96:99], v215
	ds_read_b128 v[100:103], v215 offset:1024
	ds_read_b128 v[112:115], v215 offset:2048
	ds_read_b128 v[116:119], v215 offset:3072
	ds_read_b128 v[144:147], v216
	ds_read_b128 v[148:151], v216 offset:1024
	ds_read_b128 v[152:155], v216 offset:2048
	ds_read_b128 v[156:159], v216 offset:3072
	s_add_i32 s72, s42, 2
	s_add_u32 s40, s38, 0xfff80080
	s_addc_u32 s41, s39, -1
	s_cmp_eq_u32 s33, s42
	s_cselect_b32 s42, s5, s40
	s_cselect_b32 s43, s1, s41
	s_cselect_b32 s41, s19, s71
	s_cselect_b32 s40, s21, s70
	v_lshl_add_u64 v[208:209], s[38:39], 0, v[194:195]
	s_add_i32 m0, s48, 0xc000
	ds_read_b128 v[160:163], v217
	ds_read_b128 v[164:167], v217 offset:1024
	ds_read_b128 v[168:171], v217 offset:2048
	ds_read_b128 v[172:175], v217 offset:3072
	ds_read_b128 v[176:179], v217 offset:4096
	ds_read_b128 v[180:183], v217 offset:5120
	ds_read_b128 v[200:203], v217 offset:6144
	ds_read_b128 v[204:207], v217 offset:7168
	global_load_lds_dwordx4 v[208:209], off
	v_lshl_add_u64 v[208:209], s[38:39], 0, v[196:197]
	s_add_i32 m0, s48, 0xe000
	s_nop 0
	global_load_lds_dwordx4 v[208:209], off
	s_waitcnt vmcnt(8)
	s_waitcnt lgkmcnt(0)
	s_barrier
	v_mfma_f32_16x16x32_bf16 v[140:143], v[96:99], v[160:163], 0
	v_mfma_f32_16x16x32_bf16 v[136:139], v[112:115], v[160:163], 0
	v_mfma_f32_16x16x32_bf16 v[124:127], v[96:99], v[168:171], 0
	v_mfma_f32_16x16x32_bf16 v[120:123], v[112:115], v[168:171], 0
	v_mfma_f32_16x16x32_bf16 v[92:95], v[96:99], v[176:179], 0
	v_mfma_f32_16x16x32_bf16 v[88:91], v[112:115], v[176:179], 0
	v_mfma_f32_16x16x32_bf16 v[76:79], v[96:99], v[200:203], 0
	v_mfma_f32_16x16x32_bf16 v[72:75], v[112:115], v[200:203], 0
	v_mfma_f32_16x16x32_bf16 v[140:143], v[100:103], v[164:167], v[140:143]
	v_mfma_f32_16x16x32_bf16 v[136:139], v[116:119], v[164:167], v[136:139]
	v_mfma_f32_16x16x32_bf16 v[124:127], v[100:103], v[172:175], v[124:127]
	v_mfma_f32_16x16x32_bf16 v[120:123], v[116:119], v[172:175], v[120:123]
	v_mfma_f32_16x16x32_bf16 v[92:95], v[100:103], v[180:183], v[92:95]
	v_mfma_f32_16x16x32_bf16 v[88:91], v[116:119], v[180:183], v[88:91]
	v_mfma_f32_16x16x32_bf16 v[76:79], v[100:103], v[204:207], v[76:79]
	v_mfma_f32_16x16x32_bf16 v[72:75], v[116:119], v[204:207], v[72:75]
	v_mfma_f32_16x16x32_bf16 v[132:135], v[144:147], v[160:163], 0
	v_mfma_f32_16x16x32_bf16 v[128:131], v[152:155], v[160:163], 0
	v_mfma_f32_16x16x32_bf16 v[108:111], v[144:147], v[168:171], 0
	v_mfma_f32_16x16x32_bf16 v[104:107], v[152:155], v[168:171], 0
	v_mfma_f32_16x16x32_bf16 v[84:87], v[144:147], v[176:179], 0
	v_mfma_f32_16x16x32_bf16 v[80:83], v[152:155], v[176:179], 0
	v_mfma_f32_16x16x32_bf16 v[68:71], v[144:147], v[200:203], 0
	v_mfma_f32_16x16x32_bf16 v[64:67], v[152:155], v[200:203], 0
	v_mfma_f32_16x16x32_bf16 v[132:135], v[148:151], v[164:167], v[132:135]
	v_mfma_f32_16x16x32_bf16 v[128:131], v[156:159], v[164:167], v[128:131]
	v_mfma_f32_16x16x32_bf16 v[108:111], v[148:151], v[172:175], v[108:111]
	v_mfma_f32_16x16x32_bf16 v[104:107], v[156:159], v[172:175], v[104:107]
	v_mfma_f32_16x16x32_bf16 v[84:87], v[148:151], v[180:183], v[84:87]
	v_mfma_f32_16x16x32_bf16 v[80:83], v[156:159], v[180:183], v[80:83]
	v_mfma_f32_16x16x32_bf16 v[68:71], v[148:151], v[204:207], v[68:71]
	v_mfma_f32_16x16x32_bf16 v[64:67], v[156:159], v[204:207], v[64:67]
	s_barrier
	s_add_i32 s73, s58, s17
	v_lshl_add_u64 v[208:209], s[40:41], 0, v[186:187]
	s_mov_b32 m0, s73
	ds_read_b128 v[160:163], v217 offset:16384
	ds_read_b128 v[164:167], v217 offset:17408
	ds_read_b128 v[168:171], v217 offset:18432
	ds_read_b128 v[172:175], v217 offset:19456
	ds_read_b128 v[176:179], v217 offset:20480
	ds_read_b128 v[180:183], v217 offset:21504
	ds_read_b128 v[200:203], v217 offset:22528
	ds_read_b128 v[204:207], v217 offset:23552
	global_load_lds_dwordx4 v[208:209], off
	s_add_i32 m0, s73, 0x2000
	s_add_u32 s76, s40, 0x80000
	v_lshl_add_u64 v[210:211], s[40:41], 0, v[190:191]
	s_addc_u32 s77, s41, 0
	s_add_i32 s73, s59, s17
	global_load_lds_dwordx4 v[210:211], off
	v_lshl_add_u64 v[218:219], s[76:77], 0, v[186:187]
	s_mov_b32 m0, s73
	v_lshl_add_u64 v[220:221], s[42:43], 0, v[188:189]
	global_load_lds_dwordx4 v[218:219], off
	v_lshl_add_u64 v[218:219], s[76:77], 0, v[190:191]
	s_add_i32 m0, s73, 0x2000
	s_nop 0
	global_load_lds_dwordx4 v[218:219], off
	v_lshl_add_u64 v[218:219], s[42:43], 0, v[184:185]
	s_mov_b32 m0, s48
	s_nop 0
	global_load_lds_dwordx4 v[218:219], off
	s_mov_b32 m0, s49
	s_nop 0
	global_load_lds_dwordx4 v[220:221], off
	s_waitcnt vmcnt(8)
	s_waitcnt lgkmcnt(0)
	s_barrier
; #define PG8_STAGE(bufoff, gbase, voff) do { _Pragma("unroll") for (int _i = 0; _i < 2; ++_i) \
;         __builtin_amdgcn_global_load_lds((const unsigned*)((const char*)(gbase) + (voff)[_i]), (LAS unsigned*)(lds + (bufoff) + ldsw + _i * 8192), 16, 0, 0); } while (0)
; #define PG8_LDA(dst, b, h) do { _Pragma("unroll") for (int m = 0; m < 4; ++m) _Pragma("unroll") for (int k = 0; k < 2; ++k) dst[m][k] = *(const LAS bf16x8*)(lds + PG8_SA(b, h) + aoff + m * 2048 + k * 1024); } while (0)
; #define PG8_LDB(dst, b, h) do { _Pragma("unroll") for (int n = 0; n < 2; ++n) _Pragma("unroll") for (int k = 0; k < 2; ++k) dst[n][k] = *(const LAS bf16x8*)(lds + PG8_SB(b, h) + boff + n * 2048 + k * 1024); } while (0)
; #define PG8_MMA(ai, bj, At, Bt) do { __builtin_amdgcn_s_setprio(1); _Pragma("unroll") for (int m = 0; m < 4; ++m) _Pragma("unroll") for (int n = 0; n < 2; ++n) _Pragma("unroll") for (int k = 0; k < 2; ++k) \
;         acc[ai][bj][m][n] = __builtin_amdgcn_mfma_f32_16x16x32_bf16(Bt[n][k], At[m][k], acc[ai][bj][m][n], 0, 0, 0); __builtin_amdgcn_s_setprio(0); } while (0)
; #define PG8_WAIT_V(n) asm volatile("s_waitcnt vmcnt(" #n ")" ::: "memory")
; #define PG8_WAIT_L(n) asm volatile("s_waitcnt lgkmcnt(" #n ")" ::: "memory")
; #define PG8_BAR __builtin_amdgcn_s_barrier()
; #define PG8_SCHED __builtin_amdgcn_sched_barrier(0)
; template <class Epi, class Sched = StaticOrder, class EpiSub = NoSub, bool FAST = false>
; __device__ __forceinline__ void gemm_phase(LAS unsigned char* lds, const Gemm g, const Sched& S, const Epi& E, const EpiSub& ES = EpiSub()) {
;     ...
;             PG8_WAIT_V(8); PG8_WAIT_L(0); PG8_BAR; PG8_MMA(0, 0, At, B0); PG8_MMA(0, 1, At, B1); PG8_BAR; PG8_SCHED;
;             PG8_LDA(At, 0, 1); PG8_STAGE(PG8_SB(0, 0), b2, voffB); PG8_STAGE(PG8_SB(0, 1), b2 + hstepB, voffB); PG8_STAGE(PG8_SA(0, 0), a2, voffA);
;             PG8_WAIT_V(8); PG8_WAIT_L(0); PG8_BAR; PG8_MMA(1, 0, At, B0); PG8_MMA(1, 1, At, B1); PG8_BAR; PG8_SCHED;
;             PG8_LDB(B0, 1, 0); PG8_LDB(B1, 1, 1); PG8_SCHED; PG8_LDA(At, 1, 0); PG8_STAGE(PG8_SA(0, 1), a2 + hstepA, voffA);
;             PG8_WAIT_V(8); PG8_WAIT_L(0); PG8_BAR; PG8_MMA(0, 0, At, B0); PG8_MMA(0, 1, At, B1); PG8_BAR; PG8_SCHED;
	v_mfma_f32_16x16x32_bf16 v[60:63], v[96:99], v[160:163], 0
	v_mfma_f32_16x16x32_bf16 v[56:59], v[112:115], v[160:163], 0
	v_mfma_f32_16x16x32_bf16 v[44:47], v[96:99], v[168:171], 0
	v_mfma_f32_16x16x32_bf16 v[40:43], v[112:115], v[168:171], 0
	v_mfma_f32_16x16x32_bf16 v[28:31], v[96:99], v[176:179], 0
	v_mfma_f32_16x16x32_bf16 v[24:27], v[112:115], v[176:179], 0
	v_mfma_f32_16x16x32_bf16 v[12:15], v[96:99], v[200:203], 0
	v_mfma_f32_16x16x32_bf16 v[8:11], v[112:115], v[200:203], 0
	v_mfma_f32_16x16x32_bf16 v[60:63], v[100:103], v[164:167], v[60:63]
	v_mfma_f32_16x16x32_bf16 v[56:59], v[116:119], v[164:167], v[56:59]
	v_mfma_f32_16x16x32_bf16 v[44:47], v[100:103], v[172:175], v[44:47]
	v_mfma_f32_16x16x32_bf16 v[40:43], v[116:119], v[172:175], v[40:43]
	v_mfma_f32_16x16x32_bf16 v[28:31], v[100:103], v[180:183], v[28:31]
	v_mfma_f32_16x16x32_bf16 v[24:27], v[116:119], v[180:183], v[24:27]
	v_mfma_f32_16x16x32_bf16 v[12:15], v[100:103], v[204:207], v[12:15]
	v_mfma_f32_16x16x32_bf16 v[8:11], v[116:119], v[204:207], v[8:11]
	v_mfma_f32_16x16x32_bf16 v[52:55], v[144:147], v[160:163], 0
	v_mfma_f32_16x16x32_bf16 v[48:51], v[152:155], v[160:163], 0
	v_mfma_f32_16x16x32_bf16 v[36:39], v[144:147], v[168:171], 0
	v_mfma_f32_16x16x32_bf16 v[32:35], v[152:155], v[168:171], 0
	v_mfma_f32_16x16x32_bf16 v[20:23], v[144:147], v[176:179], 0
	v_mfma_f32_16x16x32_bf16 v[16:19], v[152:155], v[176:179], 0
	v_mfma_f32_16x16x32_bf16 v[4:7], v[144:147], v[200:203], 0
	v_mfma_f32_16x16x32_bf16 v[0:3], v[152:155], v[200:203], 0
	v_mfma_f32_16x16x32_bf16 v[52:55], v[148:151], v[164:167], v[52:55]
	v_mfma_f32_16x16x32_bf16 v[48:51], v[156:159], v[164:167], v[48:51]
	v_mfma_f32_16x16x32_bf16 v[36:39], v[148:151], v[172:175], v[36:39]
	v_mfma_f32_16x16x32_bf16 v[32:35], v[156:159], v[172:175], v[32:35]
	v_mfma_f32_16x16x32_bf16 v[20:23], v[148:151], v[180:183], v[20:23]
	v_mfma_f32_16x16x32_bf16 v[16:19], v[156:159], v[180:183], v[16:19]
	v_mfma_f32_16x16x32_bf16 v[4:7], v[148:151], v[204:207], v[4:7]
	v_mfma_f32_16x16x32_bf16 v[0:3], v[156:159], v[204:207], v[0:3]
	s_barrier
	s_add_i32 s73, 0, 0x18000
	s_add_i32 s76, 0, 0x1c000
	v_add_u32_e32 v116, s73, v212
	v_add_u32_e32 v156, s76, v212
	ds_read_b128 v[96:99], v116
	ds_read_b128 v[100:103], v116 offset:1024
	ds_read_b128 v[112:115], v116 offset:2048
	ds_read_b128 v[116:119], v116 offset:3072
	ds_read_b128 v[144:147], v156
	ds_read_b128 v[148:151], v156 offset:1024
	ds_read_b128 v[152:155], v156 offset:2048
	ds_read_b128 v[156:159], v156 offset:3072
	s_add_u32 s42, s42, 0x80000
	s_addc_u32 s43, s43, 0
	s_mov_b32 m0, s50
	v_lshl_add_u64 v[222:223], s[42:43], 0, v[184:185]
	ds_read_b128 v[160:163], v217 offset:32768
	ds_read_b128 v[164:167], v217 offset:33792
	ds_read_b128 v[168:171], v217 offset:34816
	ds_read_b128 v[172:175], v217 offset:35840
	ds_read_b128 v[176:179], v217 offset:36864
	ds_read_b128 v[180:183], v217 offset:37888
	ds_read_b128 v[200:203], v217 offset:38912
	ds_read_b128 v[204:207], v217 offset:39936
	global_load_lds_dwordx4 v[222:223], off
	v_lshl_add_u64 v[222:223], s[42:43], 0, v[188:189]
	s_mov_b32 m0, s51
	s_nop 0
	global_load_lds_dwordx4 v[222:223], off
	s_waitcnt vmcnt(8)
	s_waitcnt lgkmcnt(0)
	s_barrier
	v_mfma_f32_16x16x32_bf16 v[140:143], v[96:99], v[160:163], v[140:143]
	v_mfma_f32_16x16x32_bf16 v[136:139], v[112:115], v[160:163], v[136:139]
	v_mfma_f32_16x16x32_bf16 v[124:127], v[96:99], v[168:171], v[124:127]
	v_mfma_f32_16x16x32_bf16 v[120:123], v[112:115], v[168:171], v[120:123]
	v_mfma_f32_16x16x32_bf16 v[92:95], v[96:99], v[176:179], v[92:95]
	v_mfma_f32_16x16x32_bf16 v[88:91], v[112:115], v[176:179], v[88:91]
	v_mfma_f32_16x16x32_bf16 v[76:79], v[96:99], v[200:203], v[76:79]
	v_mfma_f32_16x16x32_bf16 v[72:75], v[112:115], v[200:203], v[72:75]
	v_mfma_f32_16x16x32_bf16 v[140:143], v[100:103], v[164:167], v[140:143]
	v_mfma_f32_16x16x32_bf16 v[136:139], v[116:119], v[164:167], v[136:139]
	v_mfma_f32_16x16x32_bf16 v[124:127], v[100:103], v[172:175], v[124:127]
	v_mfma_f32_16x16x32_bf16 v[120:123], v[116:119], v[172:175], v[120:123]
	v_mfma_f32_16x16x32_bf16 v[92:95], v[100:103], v[180:183], v[92:95]
	v_mfma_f32_16x16x32_bf16 v[88:91], v[116:119], v[180:183], v[88:91]
	v_mfma_f32_16x16x32_bf16 v[76:79], v[100:103], v[204:207], v[76:79]
	v_mfma_f32_16x16x32_bf16 v[72:75], v[116:119], v[204:207], v[72:75]
	v_mfma_f32_16x16x32_bf16 v[132:135], v[144:147], v[160:163], v[132:135]
	v_mfma_f32_16x16x32_bf16 v[128:131], v[152:155], v[160:163], v[128:131]
	v_mfma_f32_16x16x32_bf16 v[108:111], v[144:147], v[168:171], v[108:111]
	v_mfma_f32_16x16x32_bf16 v[104:107], v[152:155], v[168:171], v[104:107]
	v_mfma_f32_16x16x32_bf16 v[84:87], v[144:147], v[176:179], v[84:87]
	v_mfma_f32_16x16x32_bf16 v[80:83], v[152:155], v[176:179], v[80:83]
	v_mfma_f32_16x16x32_bf16 v[68:71], v[144:147], v[200:203], v[68:71]
	v_mfma_f32_16x16x32_bf16 v[64:67], v[152:155], v[200:203], v[64:67]
	v_mfma_f32_16x16x32_bf16 v[132:135], v[148:151], v[164:167], v[132:135]
	v_mfma_f32_16x16x32_bf16 v[128:131], v[156:159], v[164:167], v[128:131]
	v_mfma_f32_16x16x32_bf16 v[108:111], v[148:151], v[172:175], v[108:111]
	v_mfma_f32_16x16x32_bf16 v[104:107], v[156:159], v[172:175], v[104:107]
	v_mfma_f32_16x16x32_bf16 v[84:87], v[148:151], v[180:183], v[84:87]
	v_mfma_f32_16x16x32_bf16 v[80:83], v[156:159], v[180:183], v[80:83]
	v_mfma_f32_16x16x32_bf16 v[68:71], v[148:151], v[204:207], v[68:71]
	v_mfma_f32_16x16x32_bf16 v[64:67], v[156:159], v[204:207], v[64:67]
	s_barrier
; #define PG8_STAGE(bufoff, gbase, voff) do { _Pragma("unroll") for (int _i = 0; _i < 2; ++_i) \
;         __builtin_amdgcn_global_load_lds((const unsigned*)((const char*)(gbase) + (voff)[_i]), (LAS unsigned*)(lds + (bufoff) + ldsw + _i * 8192), 16, 0, 0); } while (0)
; #define PG8_LDA(dst, b, h) do { _Pragma("unroll") for (int m = 0; m < 4; ++m) _Pragma("unroll") for (int k = 0; k < 2; ++k) dst[m][k] = *(const LAS bf16x8*)(lds + PG8_SA(b, h) + aoff + m * 2048 + k * 1024); } while (0)
; #define PG8_MMA(ai, bj, At, Bt) do { __builtin_amdgcn_s_setprio(1); _Pragma("unroll") for (int m = 0; m < 4; ++m) _Pragma("unroll") for (int n = 0; n < 2; ++n) _Pragma("unroll") for (int k = 0; k < 2; ++k) \
;         acc[ai][bj][m][n] = __builtin_amdgcn_mfma_f32_16x16x32_bf16(Bt[n][k], At[m][k], acc[ai][bj][m][n], 0, 0, 0); __builtin_amdgcn_s_setprio(0); } while (0)
; #define PG8_WAIT_V(n) asm volatile("s_waitcnt vmcnt(" #n ")" ::: "memory")
; #define PG8_WAIT_L(n) asm volatile("s_waitcnt lgkmcnt(" #n ")" ::: "memory")
; #define PG8_BAR __builtin_amdgcn_s_barrier()
; #define PG8_SCHED __builtin_amdgcn_sched_barrier(0)
; template <class Epi, class Sched = StaticOrder, class EpiSub = NoSub, bool FAST = false>
; __device__ __forceinline__ void gemm_phase(LAS unsigned char* lds, const Gemm g, const Sched& S, const Epi& E, const EpiSub& ES = EpiSub()) {
;     ...
;             PG8_WAIT_V(8); PG8_WAIT_L(0); PG8_BAR; PG8_MMA(0, 0, At, B0); PG8_MMA(0, 1, At, B1); PG8_BAR; PG8_SCHED;
;             PG8_LDA(At, 1, 1); PG8_STAGE(PG8_SB(1, 0), b3, voffB); PG8_STAGE(PG8_SB(1, 1), b3 + hstepB, voffB); PG8_STAGE(PG8_SA(1, 0), a3, voffA);
;             PG8_WAIT_V(8); PG8_WAIT_L(0); PG8_BAR; PG8_MMA(1, 0, At, B0); PG8_MMA(1, 1, At, B1); PG8_BAR; PG8_SCHED;
	s_add_i32 s42, s73, s17
	v_lshl_add_u64 v[208:209], v[208:209], 0, s[12:13]
	s_mov_b32 m0, s42
	ds_read_b128 v[160:163], v217 offset:49152
	ds_read_b128 v[164:167], v217 offset:50176
	ds_read_b128 v[168:171], v217 offset:51200
	ds_read_b128 v[172:175], v217 offset:52224
	ds_read_b128 v[176:179], v217 offset:53248
	ds_read_b128 v[180:183], v217 offset:54272
	ds_read_b128 v[200:203], v217 offset:55296
	ds_read_b128 v[204:207], v217 offset:56320
	global_load_lds_dwordx4 v[208:209], off
	s_add_i32 m0, s42, 0x2000
	s_add_u32 s40, s40, 0x80080
	v_lshl_add_u64 v[208:209], v[210:211], 0, s[12:13]
	s_addc_u32 s41, s41, 0
	s_add_i32 s42, s76, s17
	global_load_lds_dwordx4 v[208:209], off
	v_lshl_add_u64 v[208:209], s[40:41], 0, v[186:187]
	s_mov_b32 m0, s42
	s_nop 0
	global_load_lds_dwordx4 v[208:209], off
	v_lshl_add_u64 v[208:209], s[40:41], 0, v[190:191]
	s_add_i32 m0, s42, 0x2000
	s_nop 0
	global_load_lds_dwordx4 v[208:209], off
	v_lshl_add_u64 v[208:209], v[218:219], 0, s[12:13]
	s_mov_b32 m0, s55
	s_nop 0
	global_load_lds_dwordx4 v[208:209], off
	v_lshl_add_u64 v[208:209], v[220:221], 0, s[12:13]
	s_mov_b32 m0, s56
	s_nop 0
	global_load_lds_dwordx4 v[208:209], off
	s_waitcnt vmcnt(8)
	s_waitcnt lgkmcnt(0)
	s_barrier
	v_mfma_f32_16x16x32_bf16 v[60:63], v[96:99], v[160:163], v[60:63]
	v_mfma_f32_16x16x32_bf16 v[56:59], v[112:115], v[160:163], v[56:59]
	v_mfma_f32_16x16x32_bf16 v[44:47], v[96:99], v[168:171], v[44:47]
	v_mfma_f32_16x16x32_bf16 v[40:43], v[112:115], v[168:171], v[40:43]
	v_mfma_f32_16x16x32_bf16 v[28:31], v[96:99], v[176:179], v[28:31]
	v_mfma_f32_16x16x32_bf16 v[24:27], v[112:115], v[176:179], v[24:27]
	v_mfma_f32_16x16x32_bf16 v[12:15], v[96:99], v[200:203], v[12:15]
	v_mfma_f32_16x16x32_bf16 v[8:11], v[112:115], v[200:203], v[8:11]
	v_mfma_f32_16x16x32_bf16 v[60:63], v[100:103], v[164:167], v[60:63]
	v_mfma_f32_16x16x32_bf16 v[56:59], v[116:119], v[164:167], v[56:59]
	v_mfma_f32_16x16x32_bf16 v[44:47], v[100:103], v[172:175], v[44:47]
	v_mfma_f32_16x16x32_bf16 v[40:43], v[116:119], v[172:175], v[40:43]
	v_mfma_f32_16x16x32_bf16 v[28:31], v[100:103], v[180:183], v[28:31]
	v_mfma_f32_16x16x32_bf16 v[24:27], v[116:119], v[180:183], v[24:27]
	v_mfma_f32_16x16x32_bf16 v[12:15], v[100:103], v[204:207], v[12:15]
	v_mfma_f32_16x16x32_bf16 v[8:11], v[116:119], v[204:207], v[8:11]
	v_mfma_f32_16x16x32_bf16 v[52:55], v[144:147], v[160:163], v[52:55]
	v_mfma_f32_16x16x32_bf16 v[48:51], v[152:155], v[160:163], v[48:51]
	v_mfma_f32_16x16x32_bf16 v[36:39], v[144:147], v[168:171], v[36:39]
	v_mfma_f32_16x16x32_bf16 v[32:35], v[152:155], v[168:171], v[32:35]
	v_mfma_f32_16x16x32_bf16 v[20:23], v[144:147], v[176:179], v[20:23]
	v_mfma_f32_16x16x32_bf16 v[16:19], v[152:155], v[176:179], v[16:19]
	v_mfma_f32_16x16x32_bf16 v[4:7], v[144:147], v[200:203], v[4:7]
	v_mfma_f32_16x16x32_bf16 v[0:3], v[152:155], v[200:203], v[0:3]
	v_mfma_f32_16x16x32_bf16 v[52:55], v[148:151], v[164:167], v[52:55]
	v_mfma_f32_16x16x32_bf16 v[48:51], v[156:159], v[164:167], v[48:51]
	v_mfma_f32_16x16x32_bf16 v[36:39], v[148:151], v[172:175], v[36:39]
	v_mfma_f32_16x16x32_bf16 v[32:35], v[156:159], v[172:175], v[32:35]
	v_mfma_f32_16x16x32_bf16 v[20:23], v[148:151], v[180:183], v[20:23]
	v_mfma_f32_16x16x32_bf16 v[16:19], v[156:159], v[180:183], v[16:19]
	v_mfma_f32_16x16x32_bf16 v[4:7], v[148:151], v[204:207], v[4:7]
	v_mfma_f32_16x16x32_bf16 v[0:3], v[156:159], v[204:207], v[0:3]
	s_barrier
	s_add_u32 s38, s38, 0x100
	s_addc_u32 s39, s39, 0
	s_add_u32 s70, s70, 0x100
	s_addc_u32 s71, s71, 0
	s_cmp_ge_u32 s72, s29
	s_mov_b32 s42, s72
	s_cbranch_scc1 .Lkpeel_769_exit

; #define PG8_STAGE(bufoff, gbase, voff) do { _Pragma("unroll") for (int _i = 0; _i < 2; ++_i) \
;         __builtin_amdgcn_global_load_lds((const unsigned*)((const char*)(gbase) + (voff)[_i]), (LAS unsigned*)(lds + (bufoff) + ldsw + _i * 8192), 16, 0, 0); } while (0)
; #define PG8_LDA(dst, b, h) do { _Pragma("unroll") for (int m = 0; m < 4; ++m) _Pragma("unroll") for (int k = 0; k < 2; ++k) dst[m][k] = *(const LAS bf16x8*)(lds + PG8_SA(b, h) + aoff + m * 2048 + k * 1024); } while (0)
; #define PG8_LDB(dst, b, h) do { _Pragma("unroll") for (int n = 0; n < 2; ++n) _Pragma("unroll") for (int k = 0; k < 2; ++k) dst[n][k] = *(const LAS bf16x8*)(lds + PG8_SB(b, h) + boff + n * 2048 + k * 1024); } while (0)
; #define PG8_MMA(ai, bj, At, Bt) do { __builtin_amdgcn_s_setprio(1); _Pragma("unroll") for (int m = 0; m < 4; ++m) _Pragma("unroll") for (int n = 0; n < 2; ++n) _Pragma("unroll") for (int k = 0; k < 2; ++k) \
;         acc[ai][bj][m][n] = __builtin_amdgcn_mfma_f32_16x16x32_bf16(Bt[n][k], At[m][k], acc[ai][bj][m][n], 0, 0, 0); __builtin_amdgcn_s_setprio(0); } while (0)
; #define PG8_BAR __builtin_amdgcn_s_barrier()
; template <class Epi, class Sched = StaticOrder, class EpiSub = NoSub, bool FAST = false>
; __device__ __forceinline__ void gemm_phase(LAS unsigned char* lds, const Gemm g, const Sched& S, const Epi& E, const EpiSub& ES = EpiSub()) {
;     ...
;         const bool has_next = S.next(ui + 1, nxt);
;         const size_t nko = (has_next && nxt.kb >= 0) ? nxt.kb * ksubB : 0;
;         const char* nA = has_next ? (const char*)g.A + (size_t)nxt.pm * tstepA + (size_t)nxt.pn * g.acs + nko : cA; const char* nB = has_next ? (const char*)g.Bt + (size_t)nxt.pn * tstepB + nko : cB;
;         const int nt = cur.kb < 0 ? ntMain : ntSub;
;         for (int t = 0; t < nt; t += 2) {
;             const bool last = (t == nt - 2);
;             const char* a1 = cA + (size_t)(t + 1) * kstep;
;             const char* a2 = last ? nA : cA + (size_t)(t + 2) * kstep; const char* b2 = last ? nB : cB + (size_t)(t + 2) * kstep;
;             const char* a3 = a2 + kstep; const char* b3 = b2 + kstep;
;             if constexpr (FAST && PG8_SP2) {
;             PG8_LDB(B0, 0, 0); PG8_LDB(B1, 0, 1); PG8_SCHED; PG8_LDA(At, 0, 0); PG8_STAGE(PG8_SA(1, 1), a1 + hstepA, voffA);
;             PG8_WAIT_V(8); PG8_WAIT_L(0); PG8_BAR; PG8_MMA(0, 0, At, B0); PG8_MMA(0, 1, At, B1); PG8_BAR; PG8_SCHED;
.LBB0_984:
	s_ashr_i32 s15, s14, 31
	s_lshl_b64 s[16:17], s[14:15], 20
	v_readlane_b32 s18, v254, 36
	v_readlane_b32 s19, v254, 37
	s_add_u32 s16, s18, s16
	s_addc_u32 s17, s19, s17
	s_and_b64 s[18:19], s[0:1], exec
	s_cselect_b32 s15, s17, s23
	s_cselect_b32 s45, s16, s22
	s_ashr_i32 s13, s12, 31
	s_lshl_b64 s[18:19], s[12:13], 20
	s_add_u32 s18, s2, s18
	s_addc_u32 s19, s3, s19
	s_and_b64 s[26:27], s[0:1], exec
	s_cselect_b32 s13, s19, s25
	s_cselect_b32 s46, s18, s24
	s_add_u32 s22, s22, 0x80080
	s_addc_u32 s23, s23, 0
	s_add_u32 s47, s24, 0x100
	s_addc_u32 s48, s25, 0
	s_mov_b32 s49, -2
	s_cmp_eq_u64 s[10:11], 0
	s_cbranch_scc0 .Lkprio_985
	s_setprio 1
.Lkprio_985:
	ds_read_b128 v[150:153], v147
	ds_read_b128 v[154:157], v147 offset:1024
	ds_read_b128 v[158:161], v147 offset:2048
	ds_read_b128 v[162:165], v147 offset:3072
	ds_read_b128 v[166:169], v148
	ds_read_b128 v[170:173], v148 offset:1024
	ds_read_b128 v[174:177], v148 offset:2048
	ds_read_b128 v[178:181], v148 offset:3072
	s_add_u32 s24, s22, 0xfff80080
	s_addc_u32 s25, s23, -1
	s_cmp_eq_u32 s49, 28
	s_cselect_b32 s27, s15, s25
	s_cselect_b32 s26, s45, s24
	s_cselect_b32 s25, s13, s48
	s_cselect_b32 s24, s46, s47
	v_lshl_add_u64 v[190:191], s[22:23], 0, v[136:137]
	s_add_i32 m0, s21, 0xc000
	ds_read_b128 v[182:185], v149
	ds_read_b128 v[186:189], v149 offset:1024
	ds_read_b128 v[194:197], v149 offset:2048
	ds_read_b128 v[198:201], v149 offset:3072
	ds_read_b128 v[202:205], v149 offset:4096
	ds_read_b128 v[206:209], v149 offset:5120
	ds_read_b128 v[210:213], v149 offset:6144
	ds_read_b128 v[214:217], v149 offset:7168
	global_load_lds_dwordx4 v[190:191], off
	v_lshl_add_u64 v[190:191], s[22:23], 0, v[138:139]
	s_add_i32 m0, s21, 0xe000
	s_nop 0
	global_load_lds_dwordx4 v[190:191], off
	s_waitcnt vmcnt(8)
	s_waitcnt lgkmcnt(0)
	s_barrier
	v_mfma_f32_16x16x32_bf16 v[124:127], v[150:153], v[182:185], 0
	v_mfma_f32_16x16x32_bf16 v[116:119], v[158:161], v[182:185], 0
	v_mfma_f32_16x16x32_bf16 v[108:111], v[150:153], v[194:197], 0
	v_mfma_f32_16x16x32_bf16 v[100:103], v[158:161], v[194:197], 0
	v_mfma_f32_16x16x32_bf16 v[92:95], v[150:153], v[202:205], 0
	v_mfma_f32_16x16x32_bf16 v[84:87], v[158:161], v[202:205], 0
	v_mfma_f32_16x16x32_bf16 v[76:79], v[150:153], v[210:213], 0
	v_mfma_f32_16x16x32_bf16 v[68:71], v[158:161], v[210:213], 0
	v_mfma_f32_16x16x32_bf16 v[124:127], v[154:157], v[186:189], v[124:127]
	v_mfma_f32_16x16x32_bf16 v[116:119], v[162:165], v[186:189], v[116:119]
	v_mfma_f32_16x16x32_bf16 v[108:111], v[154:157], v[198:201], v[108:111]
	v_mfma_f32_16x16x32_bf16 v[100:103], v[162:165], v[198:201], v[100:103]
	v_mfma_f32_16x16x32_bf16 v[92:95], v[154:157], v[206:209], v[92:95]
	v_mfma_f32_16x16x32_bf16 v[84:87], v[162:165], v[206:209], v[84:87]
	v_mfma_f32_16x16x32_bf16 v[76:79], v[154:157], v[214:217], v[76:79]
	v_mfma_f32_16x16x32_bf16 v[68:71], v[162:165], v[214:217], v[68:71]
	v_mfma_f32_16x16x32_bf16 v[120:123], v[166:169], v[182:185], 0
	v_mfma_f32_16x16x32_bf16 v[112:115], v[174:177], v[182:185], 0
	v_mfma_f32_16x16x32_bf16 v[104:107], v[166:169], v[194:197], 0
	v_mfma_f32_16x16x32_bf16 v[96:99], v[174:177], v[194:197], 0
	v_mfma_f32_16x16x32_bf16 v[88:91], v[166:169], v[202:205], 0
	v_mfma_f32_16x16x32_bf16 v[80:83], v[174:177], v[202:205], 0
	v_mfma_f32_16x16x32_bf16 v[72:75], v[166:169], v[210:213], 0
	v_mfma_f32_16x16x32_bf16 v[64:67], v[174:177], v[210:213], 0
	v_mfma_f32_16x16x32_bf16 v[120:123], v[170:173], v[186:189], v[120:123]
	v_mfma_f32_16x16x32_bf16 v[112:115], v[178:181], v[186:189], v[112:115]
	v_mfma_f32_16x16x32_bf16 v[104:107], v[170:173], v[198:201], v[104:107]
	v_mfma_f32_16x16x32_bf16 v[96:99], v[178:181], v[198:201], v[96:99]
	v_mfma_f32_16x16x32_bf16 v[88:91], v[170:173], v[206:209], v[88:91]
	v_mfma_f32_16x16x32_bf16 v[80:83], v[178:181], v[206:209], v[80:83]
	v_mfma_f32_16x16x32_bf16 v[72:75], v[170:173], v[214:217], v[72:75]
	v_mfma_f32_16x16x32_bf16 v[64:67], v[178:181], v[214:217], v[64:67]
	s_barrier
	s_add_i32 s50, s42, s28
	v_lshl_add_u64 v[190:191], s[24:25], 0, v[130:131]
	s_mov_b32 m0, s50
	ds_read_b128 v[182:185], v149 offset:16384
	ds_read_b128 v[186:189], v149 offset:17408
	ds_read_b128 v[194:197], v149 offset:18432
	ds_read_b128 v[198:201], v149 offset:19456
	ds_read_b128 v[202:205], v149 offset:20480
	ds_read_b128 v[206:209], v149 offset:21504
	ds_read_b128 v[210:213], v149 offset:22528
	ds_read_b128 v[214:217], v149 offset:23552
	global_load_lds_dwordx4 v[190:191], off
	s_add_i32 m0, s50, 0x2000
	s_add_u32 s50, s24, 0x80000
	v_lshl_add_u64 v[218:219], s[24:25], 0, v[134:135]
	s_addc_u32 s51, s25, 0
	s_add_i32 s52, s43, s28
	global_load_lds_dwordx4 v[218:219], off
	v_lshl_add_u64 v[220:221], s[50:51], 0, v[130:131]
	s_mov_b32 m0, s52
	v_lshl_add_u64 v[222:223], s[26:27], 0, v[132:133]
	global_load_lds_dwordx4 v[220:221], off
	v_lshl_add_u64 v[220:221], s[50:51], 0, v[134:135]
	s_add_i32 m0, s52, 0x2000
	s_nop 0
	global_load_lds_dwordx4 v[220:221], off
	v_lshl_add_u64 v[220:221], s[26:27], 0, v[128:129]
	s_mov_b32 m0, s21
	s_nop 0
	global_load_lds_dwordx4 v[220:221], off
	s_mov_b32 m0, s31
	s_nop 0
	global_load_lds_dwordx4 v[222:223], off
	s_waitcnt vmcnt(8)
	s_waitcnt lgkmcnt(0)
	s_barrier
; #define PG8_STAGE(bufoff, gbase, voff) do { _Pragma("unroll") for (int _i = 0; _i < 2; ++_i) \
;         __builtin_amdgcn_global_load_lds((const unsigned*)((const char*)(gbase) + (voff)[_i]), (LAS unsigned*)(lds + (bufoff) + ldsw + _i * 8192), 16, 0, 0); } while (0)
; #define PG8_LDA(dst, b, h) do { _Pragma("unroll") for (int m = 0; m < 4; ++m) _Pragma("unroll") for (int k = 0; k < 2; ++k) dst[m][k] = *(const LAS bf16x8*)(lds + PG8_SA(b, h) + aoff + m * 2048 + k * 1024); } while (0)
; #define PG8_LDB(dst, b, h) do { _Pragma("unroll") for (int n = 0; n < 2; ++n) _Pragma("unroll") for (int k = 0; k < 2; ++k) dst[n][k] = *(const LAS bf16x8*)(lds + PG8_SB(b, h) + boff + n * 2048 + k * 1024); } while (0)
; #define PG8_MMA(ai, bj, At, Bt) do { __builtin_amdgcn_s_setprio(1); _Pragma("unroll") for (int m = 0; m < 4; ++m) _Pragma("unroll") for (int n = 0; n < 2; ++n) _Pragma("unroll") for (int k = 0; k < 2; ++k) \
;         acc[ai][bj][m][n] = __builtin_amdgcn_mfma_f32_16x16x32_bf16(Bt[n][k], At[m][k], acc[ai][bj][m][n], 0, 0, 0); __builtin_amdgcn_s_setprio(0); } while (0)
; #define PG8_WAIT_V(n) asm volatile("s_waitcnt vmcnt(" #n ")" ::: "memory")
; #define PG8_WAIT_L(n) asm volatile("s_waitcnt lgkmcnt(" #n ")" ::: "memory")
; #define PG8_BAR __builtin_amdgcn_s_barrier()
; #define PG8_SCHED __builtin_amdgcn_sched_barrier(0)
; template <class Epi, class Sched = StaticOrder, class EpiSub = NoSub, bool FAST = false>
; __device__ __forceinline__ void gemm_phase(LAS unsigned char* lds, const Gemm g, const Sched& S, const Epi& E, const EpiSub& ES = EpiSub()) {
;     ...
;             PG8_WAIT_V(8); PG8_WAIT_L(0); PG8_BAR; PG8_MMA(1, 0, At, B0); PG8_MMA(1, 1, At, B1); PG8_BAR; PG8_SCHED;
;             PG8_LDB(B0, 1, 0); PG8_LDB(B1, 1, 1); PG8_SCHED; PG8_LDA(At, 1, 0); PG8_STAGE(PG8_SA(0, 1), a2 + hstepA, voffA);
;             PG8_WAIT_V(8); PG8_WAIT_L(0); PG8_BAR; PG8_MMA(0, 0, At, B0); PG8_MMA(0, 1, At, B1); PG8_BAR; PG8_SCHED;
	v_mfma_f32_16x16x32_bf16 v[60:63], v[150:153], v[182:185], 0
	v_mfma_f32_16x16x32_bf16 v[52:55], v[158:161], v[182:185], 0
	v_mfma_f32_16x16x32_bf16 v[44:47], v[150:153], v[194:197], 0
	v_mfma_f32_16x16x32_bf16 v[36:39], v[158:161], v[194:197], 0
	v_mfma_f32_16x16x32_bf16 v[28:31], v[150:153], v[202:205], 0
	v_mfma_f32_16x16x32_bf16 v[20:23], v[158:161], v[202:205], 0
	v_mfma_f32_16x16x32_bf16 v[12:15], v[150:153], v[210:213], 0
	v_mfma_f32_16x16x32_bf16 v[4:7], v[158:161], v[210:213], 0
	v_mfma_f32_16x16x32_bf16 v[60:63], v[154:157], v[186:189], v[60:63]
	v_mfma_f32_16x16x32_bf16 v[52:55], v[162:165], v[186:189], v[52:55]
	v_mfma_f32_16x16x32_bf16 v[44:47], v[154:157], v[198:201], v[44:47]
	v_mfma_f32_16x16x32_bf16 v[36:39], v[162:165], v[198:201], v[36:39]
	v_mfma_f32_16x16x32_bf16 v[28:31], v[154:157], v[206:209], v[28:31]
	v_mfma_f32_16x16x32_bf16 v[20:23], v[162:165], v[206:209], v[20:23]
	v_mfma_f32_16x16x32_bf16 v[12:15], v[154:157], v[214:217], v[12:15]
	v_mfma_f32_16x16x32_bf16 v[4:7], v[162:165], v[214:217], v[4:7]
	v_mfma_f32_16x16x32_bf16 v[56:59], v[166:169], v[182:185], 0
	v_mfma_f32_16x16x32_bf16 v[48:51], v[174:177], v[182:185], 0
	v_mfma_f32_16x16x32_bf16 v[40:43], v[166:169], v[194:197], 0
	v_mfma_f32_16x16x32_bf16 v[32:35], v[174:177], v[194:197], 0
	v_mfma_f32_16x16x32_bf16 v[24:27], v[166:169], v[202:205], 0
	v_mfma_f32_16x16x32_bf16 v[16:19], v[174:177], v[202:205], 0
	v_mfma_f32_16x16x32_bf16 v[8:11], v[166:169], v[210:213], 0
	v_mfma_f32_16x16x32_bf16 v[0:3], v[174:177], v[210:213], 0
	v_mfma_f32_16x16x32_bf16 v[56:59], v[170:173], v[186:189], v[56:59]
	v_mfma_f32_16x16x32_bf16 v[48:51], v[178:181], v[186:189], v[48:51]
	v_mfma_f32_16x16x32_bf16 v[40:43], v[170:173], v[198:201], v[40:43]
	v_mfma_f32_16x16x32_bf16 v[32:35], v[178:181], v[198:201], v[32:35]
	v_mfma_f32_16x16x32_bf16 v[24:27], v[170:173], v[206:209], v[24:27]
	v_mfma_f32_16x16x32_bf16 v[16:19], v[178:181], v[206:209], v[16:19]
	v_mfma_f32_16x16x32_bf16 v[8:11], v[170:173], v[214:217], v[8:11]
	v_mfma_f32_16x16x32_bf16 v[0:3], v[178:181], v[214:217], v[0:3]
	s_barrier
	s_add_i32 s50, 0, 0x18000
	s_add_i32 s51, 0, 0x1c000
	v_add_u32_e32 v162, s50, v145
	v_add_u32_e32 v178, s51, v145
	ds_read_b128 v[150:153], v162
	ds_read_b128 v[154:157], v162 offset:1024
	ds_read_b128 v[158:161], v162 offset:2048
	ds_read_b128 v[162:165], v162 offset:3072
	ds_read_b128 v[166:169], v178
	ds_read_b128 v[170:173], v178 offset:1024
	ds_read_b128 v[174:177], v178 offset:2048
	ds_read_b128 v[178:181], v178 offset:3072
	s_add_u32 s26, s26, 0x80000
	s_addc_u32 s27, s27, 0
	s_mov_b32 m0, s36
	v_lshl_add_u64 v[224:225], s[26:27], 0, v[128:129]
	ds_read_b128 v[182:185], v149 offset:32768
	ds_read_b128 v[186:189], v149 offset:33792
	ds_read_b128 v[194:197], v149 offset:34816
	ds_read_b128 v[198:201], v149 offset:35840
	ds_read_b128 v[202:205], v149 offset:36864
	ds_read_b128 v[206:209], v149 offset:37888
	ds_read_b128 v[210:213], v149 offset:38912
	ds_read_b128 v[214:217], v149 offset:39936
	global_load_lds_dwordx4 v[224:225], off
	v_lshl_add_u64 v[224:225], s[26:27], 0, v[132:133]
	s_mov_b32 m0, s37
	s_nop 0
	global_load_lds_dwordx4 v[224:225], off
	s_waitcnt vmcnt(8)
	s_waitcnt lgkmcnt(0)
	s_barrier
	v_mfma_f32_16x16x32_bf16 v[124:127], v[150:153], v[182:185], v[124:127]
	v_mfma_f32_16x16x32_bf16 v[116:119], v[158:161], v[182:185], v[116:119]
	v_mfma_f32_16x16x32_bf16 v[108:111], v[150:153], v[194:197], v[108:111]
	v_mfma_f32_16x16x32_bf16 v[100:103], v[158:161], v[194:197], v[100:103]
	v_mfma_f32_16x16x32_bf16 v[92:95], v[150:153], v[202:205], v[92:95]
	v_mfma_f32_16x16x32_bf16 v[84:87], v[158:161], v[202:205], v[84:87]
	v_mfma_f32_16x16x32_bf16 v[76:79], v[150:153], v[210:213], v[76:79]
	v_mfma_f32_16x16x32_bf16 v[68:71], v[158:161], v[210:213], v[68:71]
	v_mfma_f32_16x16x32_bf16 v[124:127], v[154:157], v[186:189], v[124:127]
	v_mfma_f32_16x16x32_bf16 v[116:119], v[162:165], v[186:189], v[116:119]
	v_mfma_f32_16x16x32_bf16 v[108:111], v[154:157], v[198:201], v[108:111]
	v_mfma_f32_16x16x32_bf16 v[100:103], v[162:165], v[198:201], v[100:103]
	v_mfma_f32_16x16x32_bf16 v[92:95], v[154:157], v[206:209], v[92:95]
	v_mfma_f32_16x16x32_bf16 v[84:87], v[162:165], v[206:209], v[84:87]
	v_mfma_f32_16x16x32_bf16 v[76:79], v[154:157], v[214:217], v[76:79]
	v_mfma_f32_16x16x32_bf16 v[68:71], v[162:165], v[214:217], v[68:71]
	v_mfma_f32_16x16x32_bf16 v[120:123], v[166:169], v[182:185], v[120:123]
	v_mfma_f32_16x16x32_bf16 v[112:115], v[174:177], v[182:185], v[112:115]
	v_mfma_f32_16x16x32_bf16 v[104:107], v[166:169], v[194:197], v[104:107]
	v_mfma_f32_16x16x32_bf16 v[96:99], v[174:177], v[194:197], v[96:99]
	v_mfma_f32_16x16x32_bf16 v[88:91], v[166:169], v[202:205], v[88:91]
	v_mfma_f32_16x16x32_bf16 v[80:83], v[174:177], v[202:205], v[80:83]
	v_mfma_f32_16x16x32_bf16 v[72:75], v[166:169], v[210:213], v[72:75]
	v_mfma_f32_16x16x32_bf16 v[64:67], v[174:177], v[210:213], v[64:67]
	v_mfma_f32_16x16x32_bf16 v[120:123], v[170:173], v[186:189], v[120:123]
	v_mfma_f32_16x16x32_bf16 v[112:115], v[178:181], v[186:189], v[112:115]
	v_mfma_f32_16x16x32_bf16 v[104:107], v[170:173], v[198:201], v[104:107]
	v_mfma_f32_16x16x32_bf16 v[96:99], v[178:181], v[198:201], v[96:99]
	v_mfma_f32_16x16x32_bf16 v[88:91], v[170:173], v[206:209], v[88:91]
	v_mfma_f32_16x16x32_bf16 v[80:83], v[178:181], v[206:209], v[80:83]
	v_mfma_f32_16x16x32_bf16 v[72:75], v[170:173], v[214:217], v[72:75]
	v_mfma_f32_16x16x32_bf16 v[64:67], v[178:181], v[214:217], v[64:67]
	s_barrier
; #define PG8_STAGE(bufoff, gbase, voff) do { _Pragma("unroll") for (int _i = 0; _i < 2; ++_i) \
;         __builtin_amdgcn_global_load_lds((const unsigned*)((const char*)(gbase) + (voff)[_i]), (LAS unsigned*)(lds + (bufoff) + ldsw + _i * 8192), 16, 0, 0); } while (0)
; #define PG8_LDA(dst, b, h) do { _Pragma("unroll") for (int m = 0; m < 4; ++m) _Pragma("unroll") for (int k = 0; k < 2; ++k) dst[m][k] = *(const LAS bf16x8*)(lds + PG8_SA(b, h) + aoff + m * 2048 + k * 1024); } while (0)
; #define PG8_MMA(ai, bj, At, Bt) do { __builtin_amdgcn_s_setprio(1); _Pragma("unroll") for (int m = 0; m < 4; ++m) _Pragma("unroll") for (int n = 0; n < 2; ++n) _Pragma("unroll") for (int k = 0; k < 2; ++k) \
;         acc[ai][bj][m][n] = __builtin_amdgcn_mfma_f32_16x16x32_bf16(Bt[n][k], At[m][k], acc[ai][bj][m][n], 0, 0, 0); __builtin_amdgcn_s_setprio(0); } while (0)
; #define PG8_WAIT_V(n) asm volatile("s_waitcnt vmcnt(" #n ")" ::: "memory")
; #define PG8_WAIT_L(n) asm volatile("s_waitcnt lgkmcnt(" #n ")" ::: "memory")
; #define PG8_BAR __builtin_amdgcn_s_barrier()
; #define PG8_SCHED __builtin_amdgcn_sched_barrier(0)
; template <class Epi, class Sched = StaticOrder, class EpiSub = NoSub, bool FAST = false>
; __device__ __forceinline__ void gemm_phase(LAS unsigned char* lds, const Gemm g, const Sched& S, const Epi& E, const EpiSub& ES = EpiSub()) {
;     ...
;         for (int t = 0; t < nt; t += 2) {
;     ...
;             PG8_LDA(At, 1, 1); PG8_STAGE(PG8_SB(1, 0), b3, voffB); PG8_STAGE(PG8_SB(1, 1), b3 + hstepB, voffB); PG8_STAGE(PG8_SA(1, 0), a3, voffA);
;             PG8_WAIT_V(8); PG8_WAIT_L(0); PG8_BAR; PG8_MMA(1, 0, At, B0); PG8_MMA(1, 1, At, B1); PG8_BAR; PG8_SCHED;
	s_add_i32 s26, s50, s28
	v_lshl_add_u64 v[190:191], v[190:191], 0, s[8:9]
	s_mov_b32 m0, s26
	ds_read_b128 v[182:185], v149 offset:49152
	ds_read_b128 v[186:189], v149 offset:50176
	ds_read_b128 v[194:197], v149 offset:51200
	ds_read_b128 v[198:201], v149 offset:52224
	ds_read_b128 v[202:205], v149 offset:53248
	ds_read_b128 v[206:209], v149 offset:54272
	ds_read_b128 v[210:213], v149 offset:55296
	ds_read_b128 v[214:217], v149 offset:56320
	global_load_lds_dwordx4 v[190:191], off
	s_add_i32 m0, s26, 0x2000
	s_add_u32 s24, s24, 0x80080
	v_lshl_add_u64 v[190:191], v[218:219], 0, s[8:9]
	s_addc_u32 s25, s25, 0
	s_add_i32 s26, s51, s28
	global_load_lds_dwordx4 v[190:191], off
	v_lshl_add_u64 v[190:191], s[24:25], 0, v[130:131]
	s_mov_b32 m0, s26
	s_nop 0
	global_load_lds_dwordx4 v[190:191], off
	v_lshl_add_u64 v[190:191], s[24:25], 0, v[134:135]
	s_add_i32 m0, s26, 0x2000
	s_nop 0
	global_load_lds_dwordx4 v[190:191], off
	v_lshl_add_u64 v[190:191], v[220:221], 0, s[8:9]
	s_mov_b32 m0, s40
	s_nop 0
	global_load_lds_dwordx4 v[190:191], off
	v_lshl_add_u64 v[190:191], v[222:223], 0, s[8:9]
	s_mov_b32 m0, s41
	s_nop 0
	global_load_lds_dwordx4 v[190:191], off
	s_waitcnt vmcnt(8)
	s_waitcnt lgkmcnt(0)
	s_barrier
	v_mfma_f32_16x16x32_bf16 v[60:63], v[150:153], v[182:185], v[60:63]
	v_mfma_f32_16x16x32_bf16 v[52:55], v[158:161], v[182:185], v[52:55]
	v_mfma_f32_16x16x32_bf16 v[44:47], v[150:153], v[194:197], v[44:47]
	v_mfma_f32_16x16x32_bf16 v[36:39], v[158:161], v[194:197], v[36:39]
	v_mfma_f32_16x16x32_bf16 v[28:31], v[150:153], v[202:205], v[28:31]
	v_mfma_f32_16x16x32_bf16 v[20:23], v[158:161], v[202:205], v[20:23]
	v_mfma_f32_16x16x32_bf16 v[12:15], v[150:153], v[210:213], v[12:15]
	v_mfma_f32_16x16x32_bf16 v[4:7], v[158:161], v[210:213], v[4:7]
	v_mfma_f32_16x16x32_bf16 v[60:63], v[154:157], v[186:189], v[60:63]
	v_mfma_f32_16x16x32_bf16 v[52:55], v[162:165], v[186:189], v[52:55]
	v_mfma_f32_16x16x32_bf16 v[44:47], v[154:157], v[198:201], v[44:47]
	v_mfma_f32_16x16x32_bf16 v[36:39], v[162:165], v[198:201], v[36:39]
	v_mfma_f32_16x16x32_bf16 v[28:31], v[154:157], v[206:209], v[28:31]
	v_mfma_f32_16x16x32_bf16 v[20:23], v[162:165], v[206:209], v[20:23]
	v_mfma_f32_16x16x32_bf16 v[12:15], v[154:157], v[214:217], v[12:15]
	v_mfma_f32_16x16x32_bf16 v[4:7], v[162:165], v[214:217], v[4:7]
	v_mfma_f32_16x16x32_bf16 v[56:59], v[166:169], v[182:185], v[56:59]
	v_mfma_f32_16x16x32_bf16 v[48:51], v[174:177], v[182:185], v[48:51]
	v_mfma_f32_16x16x32_bf16 v[40:43], v[166:169], v[194:197], v[40:43]
	v_mfma_f32_16x16x32_bf16 v[32:35], v[174:177], v[194:197], v[32:35]
	v_mfma_f32_16x16x32_bf16 v[24:27], v[166:169], v[202:205], v[24:27]
	v_mfma_f32_16x16x32_bf16 v[16:19], v[174:177], v[202:205], v[16:19]
	v_mfma_f32_16x16x32_bf16 v[8:11], v[166:169], v[210:213], v[8:11]
	v_mfma_f32_16x16x32_bf16 v[0:3], v[174:177], v[210:213], v[0:3]
	v_mfma_f32_16x16x32_bf16 v[56:59], v[170:173], v[186:189], v[56:59]
	v_mfma_f32_16x16x32_bf16 v[48:51], v[178:181], v[186:189], v[48:51]
	v_mfma_f32_16x16x32_bf16 v[40:43], v[170:173], v[198:201], v[40:43]
	v_mfma_f32_16x16x32_bf16 v[32:35], v[178:181], v[198:201], v[32:35]
	v_mfma_f32_16x16x32_bf16 v[24:27], v[170:173], v[206:209], v[24:27]
	v_mfma_f32_16x16x32_bf16 v[16:19], v[178:181], v[206:209], v[16:19]
	v_mfma_f32_16x16x32_bf16 v[8:11], v[170:173], v[214:217], v[8:11]
	v_mfma_f32_16x16x32_bf16 v[0:3], v[178:181], v[214:217], v[0:3]
	s_barrier
	s_add_i32 s49, s49, 2
	s_add_u32 s22, s22, 0x100
	s_addc_u32 s23, s23, 0
	s_add_u32 s47, s47, 0x100
	s_addc_u32 s48, s48, 0
	s_cmp_gt_u32 s49, 29
	s_cbranch_scc1 .Lkpeel_985_exit

; #define PG8_STAGE(bufoff, gbase, voff) do { _Pragma("unroll") for (int _i = 0; _i < 2; ++_i) \
;         __builtin_amdgcn_global_load_lds((const unsigned*)((const char*)(gbase) + (voff)[_i]), (LAS unsigned*)(lds + (bufoff) + ldsw + _i * 8192), 16, 0, 0); } while (0)
; #define PG8_LDA(dst, b, h) do { _Pragma("unroll") for (int m = 0; m < 4; ++m) _Pragma("unroll") for (int k = 0; k < 2; ++k) dst[m][k] = *(const LAS bf16x8*)(lds + PG8_SA(b, h) + aoff + m * 2048 + k * 1024); } while (0)
; #define PG8_LDB(dst, b, h) do { _Pragma("unroll") for (int n = 0; n < 2; ++n) _Pragma("unroll") for (int k = 0; k < 2; ++k) dst[n][k] = *(const LAS bf16x8*)(lds + PG8_SB(b, h) + boff + n * 2048 + k * 1024); } while (0)
; #define PG8_WAIT_V(n) asm volatile("s_waitcnt vmcnt(" #n ")" ::: "memory")
; #define PG8_WAIT_L(n) asm volatile("s_waitcnt lgkmcnt(" #n ")" ::: "memory")
; #define PG8_BAR __builtin_amdgcn_s_barrier()
; #define PG8_SCHED __builtin_amdgcn_sched_barrier(0)
; template <class Epi, class Sched = StaticOrder, class EpiSub = NoSub, bool FAST = false>
; __device__ __forceinline__ void gemm_phase(LAS unsigned char* lds, const Gemm g, const Sched& S, const Epi& E, const EpiSub& ES = EpiSub()) {
;     ...
;         const bool has_next = S.next(ui + 1, nxt);
;         const size_t nko = (has_next && nxt.kb >= 0) ? nxt.kb * ksubB : 0;
;         const char* nA = has_next ? (const char*)g.A + (size_t)nxt.pm * tstepA + (size_t)nxt.pn * g.acs + nko : cA; const char* nB = has_next ? (const char*)g.Bt + (size_t)nxt.pn * tstepB + nko : cB;
;         const int nt = cur.kb < 0 ? ntMain : ntSub;
;         for (int t = 0; t < nt; t += 2) {
;             const bool last = (t == nt - 2);
;             const char* a1 = cA + (size_t)(t + 1) * kstep;
;             const char* a2 = last ? nA : cA + (size_t)(t + 2) * kstep; const char* b2 = last ? nB : cB + (size_t)(t + 2) * kstep;
;             const char* a3 = a2 + kstep; const char* b3 = b2 + kstep;
;             if constexpr (FAST && PG8_SP2) {
;             PG8_LDB(B0, 0, 0); PG8_LDB(B1, 0, 1); PG8_SCHED; PG8_LDA(At, 0, 0); PG8_STAGE(PG8_SA(1, 1), a1 + hstepA, voffA);
;             PG8_WAIT_V(8); PG8_WAIT_L(0); PG8_BAR; PG8_MMA(0, 0, At, B0); PG8_MMA(0, 1, At, B1); PG8_BAR; PG8_SCHED;
;             PG8_LDA(At, 0, 1); PG8_STAGE(PG8_SB(0, 0), b2, voffB); PG8_STAGE(PG8_SB(0, 1), b2 + hstepB, voffB); PG8_STAGE(PG8_SA(0, 0), a2, voffA);
.LBB0_1078:
	s_cmp_gt_i32 s8, -1
	s_cselect_b64 s[4:5], -1, 0
	s_cmp_lt_i32 s8, 0
	s_cselect_b32 s70, 0x58, 22
	s_add_i32 s71, s70, -2
	s_add_u32 s42, s42, 0x160080
	s_addc_u32 s43, s43, 0
	s_add_u32 s83, s44, 0x100
	s_mov_b32 s46, 0
	s_addc_u32 s84, s45, 0
	s_cmp_eq_u64 s[18:19], 0
	s_cbranch_scc0 .Lkprio_1079
	s_setprio 1
.Lkprio_1079:
	ds_read_b128 v[96:99], v201
	ds_read_b128 v[100:103], v201 offset:1024
	ds_read_b128 v[108:111], v201 offset:2048
	ds_read_b128 v[116:119], v201 offset:3072
	ds_read_b128 v[144:147], v202
	ds_read_b128 v[148:151], v202 offset:1024
	ds_read_b128 v[152:155], v202 offset:2048
	ds_read_b128 v[156:159], v202 offset:3072
	s_add_i32 s85, s46, 2
	s_add_u32 s44, s42, 0xffea0080
	s_addc_u32 s45, s43, -1
	s_cmp_eq_u32 s71, s46
	s_cselect_b32 s46, s38, s44
	s_cselect_b32 s47, s39, s45
	s_cselect_b32 s45, s41, s84
	s_cselect_b32 s44, s40, s83
	v_lshl_add_u64 v[190:191], s[42:43], 0, v[176:177]
	s_add_i32 m0, s48, 0xc000
	ds_read_b128 v[160:163], v203
	ds_read_b128 v[164:167], v203 offset:1024
	ds_read_b128 v[182:185], v203 offset:2048
	ds_read_b128 v[186:189], v203 offset:3072
	ds_read_b128 v[194:197], v203 offset:4096
	ds_read_b128 v[204:207], v203 offset:5120
	ds_read_b128 v[208:211], v203 offset:6144
	ds_read_b128 v[212:215], v203 offset:7168
	global_load_lds_dwordx4 v[190:191], off
	v_lshl_add_u64 v[190:191], s[42:43], 0, v[178:179]
	s_add_i32 m0, s48, 0xe000
	s_nop 0
	global_load_lds_dwordx4 v[190:191], off
	s_waitcnt vmcnt(8)
	s_waitcnt lgkmcnt(0)
	s_barrier
	v_mfma_f32_16x16x32_bf16 v[140:143], v[96:99], v[160:163], 0
	v_mfma_f32_16x16x32_bf16 v[136:139], v[108:111], v[160:163], 0
	v_mfma_f32_16x16x32_bf16 v[124:127], v[96:99], v[182:185], 0
	v_mfma_f32_16x16x32_bf16 v[120:123], v[108:111], v[182:185], 0
	v_mfma_f32_16x16x32_bf16 v[92:95], v[96:99], v[194:197], 0
	v_mfma_f32_16x16x32_bf16 v[88:91], v[108:111], v[194:197], 0
	v_mfma_f32_16x16x32_bf16 v[76:79], v[96:99], v[208:211], 0
	v_mfma_f32_16x16x32_bf16 v[72:75], v[108:111], v[208:211], 0
	v_mfma_f32_16x16x32_bf16 v[140:143], v[100:103], v[164:167], v[140:143]
	v_mfma_f32_16x16x32_bf16 v[136:139], v[116:119], v[164:167], v[136:139]
	v_mfma_f32_16x16x32_bf16 v[124:127], v[100:103], v[186:189], v[124:127]
	v_mfma_f32_16x16x32_bf16 v[120:123], v[116:119], v[186:189], v[120:123]
	v_mfma_f32_16x16x32_bf16 v[92:95], v[100:103], v[204:207], v[92:95]
	v_mfma_f32_16x16x32_bf16 v[88:91], v[116:119], v[204:207], v[88:91]
	v_mfma_f32_16x16x32_bf16 v[76:79], v[100:103], v[212:215], v[76:79]
	v_mfma_f32_16x16x32_bf16 v[72:75], v[116:119], v[212:215], v[72:75]
	v_mfma_f32_16x16x32_bf16 v[132:135], v[144:147], v[160:163], 0
	v_mfma_f32_16x16x32_bf16 v[128:131], v[152:155], v[160:163], 0
	v_mfma_f32_16x16x32_bf16 v[112:115], v[144:147], v[182:185], 0
	v_mfma_f32_16x16x32_bf16 v[104:107], v[152:155], v[182:185], 0
	v_mfma_f32_16x16x32_bf16 v[84:87], v[144:147], v[194:197], 0
	v_mfma_f32_16x16x32_bf16 v[80:83], v[152:155], v[194:197], 0
	v_mfma_f32_16x16x32_bf16 v[68:71], v[144:147], v[208:211], 0
	v_mfma_f32_16x16x32_bf16 v[64:67], v[152:155], v[208:211], 0
	v_mfma_f32_16x16x32_bf16 v[132:135], v[148:151], v[164:167], v[132:135]
	v_mfma_f32_16x16x32_bf16 v[128:131], v[156:159], v[164:167], v[128:131]
	v_mfma_f32_16x16x32_bf16 v[112:115], v[148:151], v[186:189], v[112:115]
	v_mfma_f32_16x16x32_bf16 v[104:107], v[156:159], v[186:189], v[104:107]
	v_mfma_f32_16x16x32_bf16 v[84:87], v[148:151], v[204:207], v[84:87]
	v_mfma_f32_16x16x32_bf16 v[80:83], v[156:159], v[204:207], v[80:83]
	v_mfma_f32_16x16x32_bf16 v[68:71], v[148:151], v[212:215], v[68:71]
	v_mfma_f32_16x16x32_bf16 v[64:67], v[156:159], v[212:215], v[64:67]
	s_barrier
	s_add_i32 s86, s58, s27
	v_lshl_add_u64 v[190:191], s[44:45], 0, v[170:171]
	s_mov_b32 m0, s86
	ds_read_b128 v[160:163], v203 offset:16384
	ds_read_b128 v[164:167], v203 offset:17408
	ds_read_b128 v[182:185], v203 offset:18432
	ds_read_b128 v[186:189], v203 offset:19456
	ds_read_b128 v[194:197], v203 offset:20480
	ds_read_b128 v[204:207], v203 offset:21504
	ds_read_b128 v[208:211], v203 offset:22528
	ds_read_b128 v[212:215], v203 offset:23552
	global_load_lds_dwordx4 v[190:191], off
	s_add_i32 m0, s86, 0x2000
	s_add_u32 s86, s44, 0x160000
	v_lshl_add_u64 v[216:217], s[44:45], 0, v[174:175]
	s_addc_u32 s87, s45, 0
	s_add_i32 s88, s59, s27
	global_load_lds_dwordx4 v[216:217], off
	v_lshl_add_u64 v[218:219], s[86:87], 0, v[170:171]
	s_mov_b32 m0, s88
	v_lshl_add_u64 v[220:221], s[46:47], 0, v[172:173]
	global_load_lds_dwordx4 v[218:219], off
	v_lshl_add_u64 v[218:219], s[86:87], 0, v[174:175]
	s_add_i32 m0, s88, 0x2000
	s_nop 0
	global_load_lds_dwordx4 v[218:219], off
	v_lshl_add_u64 v[218:219], s[46:47], 0, v[168:169]
	s_mov_b32 m0, s48
	s_nop 0
	global_load_lds_dwordx4 v[218:219], off
	s_mov_b32 m0, s49
	s_nop 0
	global_load_lds_dwordx4 v[220:221], off
	s_waitcnt vmcnt(8)
	s_waitcnt lgkmcnt(0)
	s_barrier
; #define PG8_STAGE(bufoff, gbase, voff) do { _Pragma("unroll") for (int _i = 0; _i < 2; ++_i) \
;         __builtin_amdgcn_global_load_lds((const unsigned*)((const char*)(gbase) + (voff)[_i]), (LAS unsigned*)(lds + (bufoff) + ldsw + _i * 8192), 16, 0, 0); } while (0)
; #define PG8_LDA(dst, b, h) do { _Pragma("unroll") for (int m = 0; m < 4; ++m) _Pragma("unroll") for (int k = 0; k < 2; ++k) dst[m][k] = *(const LAS bf16x8*)(lds + PG8_SA(b, h) + aoff + m * 2048 + k * 1024); } while (0)
; #define PG8_LDB(dst, b, h) do { _Pragma("unroll") for (int n = 0; n < 2; ++n) _Pragma("unroll") for (int k = 0; k < 2; ++k) dst[n][k] = *(const LAS bf16x8*)(lds + PG8_SB(b, h) + boff + n * 2048 + k * 1024); } while (0)
; #define PG8_MMA(ai, bj, At, Bt) do { __builtin_amdgcn_s_setprio(1); _Pragma("unroll") for (int m = 0; m < 4; ++m) _Pragma("unroll") for (int n = 0; n < 2; ++n) _Pragma("unroll") for (int k = 0; k < 2; ++k) \
;         acc[ai][bj][m][n] = __builtin_amdgcn_mfma_f32_16x16x32_bf16(Bt[n][k], At[m][k], acc[ai][bj][m][n], 0, 0, 0); __builtin_amdgcn_s_setprio(0); } while (0)
; #define PG8_WAIT_V(n) asm volatile("s_waitcnt vmcnt(" #n ")" ::: "memory")
; #define PG8_WAIT_L(n) asm volatile("s_waitcnt lgkmcnt(" #n ")" ::: "memory")
; #define PG8_BAR __builtin_amdgcn_s_barrier()
; #define PG8_SCHED __builtin_amdgcn_sched_barrier(0)
; template <class Epi, class Sched = StaticOrder, class EpiSub = NoSub, bool FAST = false>
; __device__ __forceinline__ void gemm_phase(LAS unsigned char* lds, const Gemm g, const Sched& S, const Epi& E, const EpiSub& ES = EpiSub()) {
;     ...
;             PG8_WAIT_V(8); PG8_WAIT_L(0); PG8_BAR; PG8_MMA(1, 0, At, B0); PG8_MMA(1, 1, At, B1); PG8_BAR; PG8_SCHED;
;             PG8_LDB(B0, 1, 0); PG8_LDB(B1, 1, 1); PG8_SCHED; PG8_LDA(At, 1, 0); PG8_STAGE(PG8_SA(0, 1), a2 + hstepA, voffA);
;             PG8_WAIT_V(8); PG8_WAIT_L(0); PG8_BAR; PG8_MMA(0, 0, At, B0); PG8_MMA(0, 1, At, B1); PG8_BAR; PG8_SCHED;
	v_mfma_f32_16x16x32_bf16 v[60:63], v[96:99], v[160:163], 0
	v_mfma_f32_16x16x32_bf16 v[56:59], v[108:111], v[160:163], 0
	v_mfma_f32_16x16x32_bf16 v[44:47], v[96:99], v[182:185], 0
	v_mfma_f32_16x16x32_bf16 v[40:43], v[108:111], v[182:185], 0
	v_mfma_f32_16x16x32_bf16 v[28:31], v[96:99], v[194:197], 0
	v_mfma_f32_16x16x32_bf16 v[24:27], v[108:111], v[194:197], 0
	v_mfma_f32_16x16x32_bf16 v[12:15], v[96:99], v[208:211], 0
	v_mfma_f32_16x16x32_bf16 v[8:11], v[108:111], v[208:211], 0
	v_mfma_f32_16x16x32_bf16 v[60:63], v[100:103], v[164:167], v[60:63]
	v_mfma_f32_16x16x32_bf16 v[56:59], v[116:119], v[164:167], v[56:59]
	v_mfma_f32_16x16x32_bf16 v[44:47], v[100:103], v[186:189], v[44:47]
	v_mfma_f32_16x16x32_bf16 v[40:43], v[116:119], v[186:189], v[40:43]
	v_mfma_f32_16x16x32_bf16 v[28:31], v[100:103], v[204:207], v[28:31]
	v_mfma_f32_16x16x32_bf16 v[24:27], v[116:119], v[204:207], v[24:27]
	v_mfma_f32_16x16x32_bf16 v[12:15], v[100:103], v[212:215], v[12:15]
	v_mfma_f32_16x16x32_bf16 v[8:11], v[116:119], v[212:215], v[8:11]
	v_mfma_f32_16x16x32_bf16 v[52:55], v[144:147], v[160:163], 0
	v_mfma_f32_16x16x32_bf16 v[48:51], v[152:155], v[160:163], 0
	v_mfma_f32_16x16x32_bf16 v[36:39], v[144:147], v[182:185], 0
	v_mfma_f32_16x16x32_bf16 v[32:35], v[152:155], v[182:185], 0
	v_mfma_f32_16x16x32_bf16 v[20:23], v[144:147], v[194:197], 0
	v_mfma_f32_16x16x32_bf16 v[16:19], v[152:155], v[194:197], 0
	v_mfma_f32_16x16x32_bf16 v[4:7], v[144:147], v[208:211], 0
	v_mfma_f32_16x16x32_bf16 v[0:3], v[152:155], v[208:211], 0
	v_mfma_f32_16x16x32_bf16 v[52:55], v[148:151], v[164:167], v[52:55]
	v_mfma_f32_16x16x32_bf16 v[48:51], v[156:159], v[164:167], v[48:51]
	v_mfma_f32_16x16x32_bf16 v[36:39], v[148:151], v[186:189], v[36:39]
	v_mfma_f32_16x16x32_bf16 v[32:35], v[156:159], v[186:189], v[32:35]
	v_mfma_f32_16x16x32_bf16 v[20:23], v[148:151], v[204:207], v[20:23]
	v_mfma_f32_16x16x32_bf16 v[16:19], v[156:159], v[204:207], v[16:19]
	v_mfma_f32_16x16x32_bf16 v[4:7], v[148:151], v[212:215], v[4:7]
	v_mfma_f32_16x16x32_bf16 v[0:3], v[156:159], v[212:215], v[0:3]
	s_barrier
	s_add_i32 s86, 0, 0x18000
	s_add_i32 s87, 0, 0x1c000
	v_add_u32_e32 v116, s86, v198
	v_add_u32_e32 v156, s87, v198
	ds_read_b128 v[96:99], v116
	ds_read_b128 v[100:103], v116 offset:1024
	ds_read_b128 v[108:111], v116 offset:2048
	ds_read_b128 v[116:119], v116 offset:3072
	ds_read_b128 v[144:147], v156
	ds_read_b128 v[148:151], v156 offset:1024
	ds_read_b128 v[152:155], v156 offset:2048
	ds_read_b128 v[156:159], v156 offset:3072
	s_add_u32 s46, s46, 0x160000
	s_addc_u32 s47, s47, 0
	s_mov_b32 m0, s50
	v_lshl_add_u64 v[222:223], s[46:47], 0, v[168:169]
	ds_read_b128 v[160:163], v203 offset:32768
	ds_read_b128 v[164:167], v203 offset:33792
	ds_read_b128 v[182:185], v203 offset:34816
	ds_read_b128 v[186:189], v203 offset:35840
	ds_read_b128 v[194:197], v203 offset:36864
	ds_read_b128 v[204:207], v203 offset:37888
	ds_read_b128 v[208:211], v203 offset:38912
	ds_read_b128 v[212:215], v203 offset:39936
	global_load_lds_dwordx4 v[222:223], off
	v_lshl_add_u64 v[222:223], s[46:47], 0, v[172:173]
	s_mov_b32 m0, s51
	s_nop 0
	global_load_lds_dwordx4 v[222:223], off
	s_waitcnt vmcnt(8)
	s_waitcnt lgkmcnt(0)
	s_barrier
	v_mfma_f32_16x16x32_bf16 v[140:143], v[96:99], v[160:163], v[140:143]
	v_mfma_f32_16x16x32_bf16 v[136:139], v[108:111], v[160:163], v[136:139]
	v_mfma_f32_16x16x32_bf16 v[124:127], v[96:99], v[182:185], v[124:127]
	v_mfma_f32_16x16x32_bf16 v[120:123], v[108:111], v[182:185], v[120:123]
	v_mfma_f32_16x16x32_bf16 v[92:95], v[96:99], v[194:197], v[92:95]
	v_mfma_f32_16x16x32_bf16 v[88:91], v[108:111], v[194:197], v[88:91]
	v_mfma_f32_16x16x32_bf16 v[76:79], v[96:99], v[208:211], v[76:79]
	v_mfma_f32_16x16x32_bf16 v[72:75], v[108:111], v[208:211], v[72:75]
	v_mfma_f32_16x16x32_bf16 v[140:143], v[100:103], v[164:167], v[140:143]
	v_mfma_f32_16x16x32_bf16 v[136:139], v[116:119], v[164:167], v[136:139]
	v_mfma_f32_16x16x32_bf16 v[124:127], v[100:103], v[186:189], v[124:127]
	v_mfma_f32_16x16x32_bf16 v[120:123], v[116:119], v[186:189], v[120:123]
	v_mfma_f32_16x16x32_bf16 v[92:95], v[100:103], v[204:207], v[92:95]
	v_mfma_f32_16x16x32_bf16 v[88:91], v[116:119], v[204:207], v[88:91]
	v_mfma_f32_16x16x32_bf16 v[76:79], v[100:103], v[212:215], v[76:79]
	v_mfma_f32_16x16x32_bf16 v[72:75], v[116:119], v[212:215], v[72:75]
	v_mfma_f32_16x16x32_bf16 v[132:135], v[144:147], v[160:163], v[132:135]
	v_mfma_f32_16x16x32_bf16 v[128:131], v[152:155], v[160:163], v[128:131]
	v_mfma_f32_16x16x32_bf16 v[112:115], v[144:147], v[182:185], v[112:115]
	v_mfma_f32_16x16x32_bf16 v[104:107], v[152:155], v[182:185], v[104:107]
	v_mfma_f32_16x16x32_bf16 v[84:87], v[144:147], v[194:197], v[84:87]
	v_mfma_f32_16x16x32_bf16 v[80:83], v[152:155], v[194:197], v[80:83]
	v_mfma_f32_16x16x32_bf16 v[68:71], v[144:147], v[208:211], v[68:71]
	v_mfma_f32_16x16x32_bf16 v[64:67], v[152:155], v[208:211], v[64:67]
	v_mfma_f32_16x16x32_bf16 v[132:135], v[148:151], v[164:167], v[132:135]
	v_mfma_f32_16x16x32_bf16 v[128:131], v[156:159], v[164:167], v[128:131]
	v_mfma_f32_16x16x32_bf16 v[112:115], v[148:151], v[186:189], v[112:115]
	v_mfma_f32_16x16x32_bf16 v[104:107], v[156:159], v[186:189], v[104:107]
	v_mfma_f32_16x16x32_bf16 v[84:87], v[148:151], v[204:207], v[84:87]
	v_mfma_f32_16x16x32_bf16 v[80:83], v[156:159], v[204:207], v[80:83]
	v_mfma_f32_16x16x32_bf16 v[68:71], v[148:151], v[212:215], v[68:71]
	v_mfma_f32_16x16x32_bf16 v[64:67], v[156:159], v[212:215], v[64:67]
	s_barrier
; #define PG8_STAGE(bufoff, gbase, voff) do { _Pragma("unroll") for (int _i = 0; _i < 2; ++_i) \
;         __builtin_amdgcn_global_load_lds((const unsigned*)((const char*)(gbase) + (voff)[_i]), (LAS unsigned*)(lds + (bufoff) + ldsw + _i * 8192), 16, 0, 0); } while (0)
; #define PG8_LDA(dst, b, h) do { _Pragma("unroll") for (int m = 0; m < 4; ++m) _Pragma("unroll") for (int k = 0; k < 2; ++k) dst[m][k] = *(const LAS bf16x8*)(lds + PG8_SA(b, h) + aoff + m * 2048 + k * 1024); } while (0)
; #define PG8_MMA(ai, bj, At, Bt) do { __builtin_amdgcn_s_setprio(1); _Pragma("unroll") for (int m = 0; m < 4; ++m) _Pragma("unroll") for (int n = 0; n < 2; ++n) _Pragma("unroll") for (int k = 0; k < 2; ++k) \
;         acc[ai][bj][m][n] = __builtin_amdgcn_mfma_f32_16x16x32_bf16(Bt[n][k], At[m][k], acc[ai][bj][m][n], 0, 0, 0); __builtin_amdgcn_s_setprio(0); } while (0)
; #define PG8_WAIT_V(n) asm volatile("s_waitcnt vmcnt(" #n ")" ::: "memory")
; #define PG8_WAIT_L(n) asm volatile("s_waitcnt lgkmcnt(" #n ")" ::: "memory")
; #define PG8_BAR __builtin_amdgcn_s_barrier()
; #define PG8_SCHED __builtin_amdgcn_sched_barrier(0)
; template <class Epi, class Sched = StaticOrder, class EpiSub = NoSub, bool FAST = false>
; __device__ __forceinline__ void gemm_phase(LAS unsigned char* lds, const Gemm g, const Sched& S, const Epi& E, const EpiSub& ES = EpiSub()) {
;     ...
;             PG8_LDA(At, 1, 1); PG8_STAGE(PG8_SB(1, 0), b3, voffB); PG8_STAGE(PG8_SB(1, 1), b3 + hstepB, voffB); PG8_STAGE(PG8_SA(1, 0), a3, voffA);
;             PG8_WAIT_V(8); PG8_WAIT_L(0); PG8_BAR; PG8_MMA(1, 0, At, B0); PG8_MMA(1, 1, At, B1); PG8_BAR; PG8_SCHED;
	s_add_i32 s46, s86, s27
	v_lshl_add_u64 v[190:191], v[190:191], 0, s[16:17]
	s_mov_b32 m0, s46
	ds_read_b128 v[160:163], v203 offset:49152
	ds_read_b128 v[164:167], v203 offset:50176
	ds_read_b128 v[182:185], v203 offset:51200
	ds_read_b128 v[186:189], v203 offset:52224
	ds_read_b128 v[194:197], v203 offset:53248
	ds_read_b128 v[204:207], v203 offset:54272
	ds_read_b128 v[208:211], v203 offset:55296
	ds_read_b128 v[212:215], v203 offset:56320
	global_load_lds_dwordx4 v[190:191], off
	s_add_i32 m0, s46, 0x2000
	s_add_u32 s44, s44, 0x160080
	v_lshl_add_u64 v[190:191], v[216:217], 0, s[16:17]
	s_addc_u32 s45, s45, 0
	s_add_i32 s46, s87, s27
	global_load_lds_dwordx4 v[190:191], off
	v_lshl_add_u64 v[190:191], s[44:45], 0, v[170:171]
	s_mov_b32 m0, s46
	s_nop 0
	global_load_lds_dwordx4 v[190:191], off
	v_lshl_add_u64 v[190:191], s[44:45], 0, v[174:175]
	s_add_i32 m0, s46, 0x2000
	s_nop 0
	global_load_lds_dwordx4 v[190:191], off
	v_lshl_add_u64 v[190:191], v[218:219], 0, s[16:17]
	s_mov_b32 m0, s53
	s_nop 0
	global_load_lds_dwordx4 v[190:191], off
	v_lshl_add_u64 v[190:191], v[220:221], 0, s[16:17]
	s_mov_b32 m0, s54
	s_nop 0
	global_load_lds_dwordx4 v[190:191], off
	s_waitcnt vmcnt(8)
	s_waitcnt lgkmcnt(0)
	s_barrier
	v_mfma_f32_16x16x32_bf16 v[60:63], v[96:99], v[160:163], v[60:63]
	v_mfma_f32_16x16x32_bf16 v[56:59], v[108:111], v[160:163], v[56:59]
	v_mfma_f32_16x16x32_bf16 v[44:47], v[96:99], v[182:185], v[44:47]
	v_mfma_f32_16x16x32_bf16 v[40:43], v[108:111], v[182:185], v[40:43]
	v_mfma_f32_16x16x32_bf16 v[28:31], v[96:99], v[194:197], v[28:31]
	v_mfma_f32_16x16x32_bf16 v[24:27], v[108:111], v[194:197], v[24:27]
	v_mfma_f32_16x16x32_bf16 v[12:15], v[96:99], v[208:211], v[12:15]
	v_mfma_f32_16x16x32_bf16 v[8:11], v[108:111], v[208:211], v[8:11]
	v_mfma_f32_16x16x32_bf16 v[60:63], v[100:103], v[164:167], v[60:63]
	v_mfma_f32_16x16x32_bf16 v[56:59], v[116:119], v[164:167], v[56:59]
	v_mfma_f32_16x16x32_bf16 v[44:47], v[100:103], v[186:189], v[44:47]
	v_mfma_f32_16x16x32_bf16 v[40:43], v[116:119], v[186:189], v[40:43]
	v_mfma_f32_16x16x32_bf16 v[28:31], v[100:103], v[204:207], v[28:31]
	v_mfma_f32_16x16x32_bf16 v[24:27], v[116:119], v[204:207], v[24:27]
	v_mfma_f32_16x16x32_bf16 v[12:15], v[100:103], v[212:215], v[12:15]
	v_mfma_f32_16x16x32_bf16 v[8:11], v[116:119], v[212:215], v[8:11]
	v_mfma_f32_16x16x32_bf16 v[52:55], v[144:147], v[160:163], v[52:55]
	v_mfma_f32_16x16x32_bf16 v[48:51], v[152:155], v[160:163], v[48:51]
	v_mfma_f32_16x16x32_bf16 v[36:39], v[144:147], v[182:185], v[36:39]
	v_mfma_f32_16x16x32_bf16 v[32:35], v[152:155], v[182:185], v[32:35]
	v_mfma_f32_16x16x32_bf16 v[20:23], v[144:147], v[194:197], v[20:23]
	v_mfma_f32_16x16x32_bf16 v[16:19], v[152:155], v[194:197], v[16:19]
	v_mfma_f32_16x16x32_bf16 v[4:7], v[144:147], v[208:211], v[4:7]
	v_mfma_f32_16x16x32_bf16 v[0:3], v[152:155], v[208:211], v[0:3]
	v_mfma_f32_16x16x32_bf16 v[52:55], v[148:151], v[164:167], v[52:55]
	v_mfma_f32_16x16x32_bf16 v[48:51], v[156:159], v[164:167], v[48:51]
	v_mfma_f32_16x16x32_bf16 v[36:39], v[148:151], v[186:189], v[36:39]
	v_mfma_f32_16x16x32_bf16 v[32:35], v[156:159], v[186:189], v[32:35]
	v_mfma_f32_16x16x32_bf16 v[20:23], v[148:151], v[204:207], v[20:23]
	v_mfma_f32_16x16x32_bf16 v[16:19], v[156:159], v[204:207], v[16:19]
	v_mfma_f32_16x16x32_bf16 v[4:7], v[148:151], v[212:215], v[4:7]
	v_mfma_f32_16x16x32_bf16 v[0:3], v[156:159], v[212:215], v[0:3]
	s_barrier
	s_add_u32 s42, s42, 0x100
	s_addc_u32 s43, s43, 0
	s_add_u32 s83, s83, 0x100
	s_addc_u32 s84, s84, 0
	s_cmp_ge_u32 s85, s70
	s_mov_b32 s46, s85
	s_cbranch_scc1 .Lkpeel_1079_exit
